# hgrn stage-1 and stage-2 state stores as agent-scope write-through (sc1) stores; wave 0's buffer_wbl2 before the two hgrn sub-barrier arrives removed
# speedup vs baseline: 1.0060x; 1.0060x over previous
.LBB0_431:
	s_ashr_i32 s21, s20, 31
	s_lshl_b64 s[0:1], s[20:21], 9
	v_readlane_b32 s4, v254, 46
	v_readlane_b32 s5, v254, 47
	s_add_u32 s0, s4, s0
	s_addc_u32 s1, s5, s1
	s_lshl_b32 s3, s33, 5
	s_and_b32 s3, s3, 0xc0
	s_lshl_b32 s4, s3, 1
	s_add_u32 s0, s0, s4
	s_addc_u32 s1, s1, 0
	v_ashrrev_i32_e32 v35, 31, v34
	s_ashr_i32 s37, s36, 31
	v_lshl_add_u64 v[30:31], v[34:35], 1, s[0:1]
	s_lshl_b64 s[0:1], s[36:37], 9
	v_lshl_add_u64 v[2:3], v[30:31], 0, s[0:1]
	global_load_ushort v100, v[30:31], off
	s_lshl_b32 s0, s36, 1
	global_load_ushort v101, v[2:3], off
	s_ashr_i32 s1, s0, 31
	s_mul_i32 s90, s36, 15
	v_writelane_b32 v255, s0, 0
	s_ashr_i32 s91, s90, 31
	s_mul_i32 s12, s36, 21
	v_writelane_b32 v255, s1, 1
	s_lshl_b64 s[0:1], s[0:1], 9
	v_lshl_add_u64 v[4:5], v[30:31], 0, s[0:1]
	s_mul_i32 s0, s36, 3
	s_ashr_i32 s1, s0, 31
	v_writelane_b32 v255, s0, 2
	s_ashr_i32 s13, s12, 31
	s_mul_i32 s34, s36, 22
	v_writelane_b32 v255, s1, 3
	s_lshl_b64 s[0:1], s[0:1], 9
	s_ashr_i32 s35, s34, 31
	s_mul_i32 s28, s36, 23
	s_ashr_i32 s29, s28, 31
	s_mul_i32 s14, s36, 24
	s_ashr_i32 s15, s14, 31
	s_mul_i32 s96, s36, 25
	s_ashr_i32 s97, s96, 31
	s_mul_i32 s52, s36, 26
	s_ashr_i32 s53, s52, 31
	s_mul_i32 s16, s36, 27
	s_ashr_i32 s17, s16, 31
	s_mul_i32 s4, s36, 28
	s_ashr_i32 s5, s4, 31
	s_mul_i32 s92, s36, 29
	s_ashr_i32 s93, s92, 31
	s_mul_i32 s38, s36, 30
	s_ashr_i32 s39, s38, 31
	s_mul_i32 s18, s36, 31
	s_ashr_i32 s19, s18, 31
	s_lshl_b32 s22, s36, 5
	s_ashr_i32 s23, s22, 31
	s_mul_i32 s24, s36, 33
	s_ashr_i32 s25, s24, 31
	s_mul_i32 s30, s36, 34
	s_ashr_i32 s31, s30, 31
	s_mul_i32 s6, s36, 35
	s_ashr_i32 s7, s6, 31
	s_mul_i32 s72, s36, 36
	s_ashr_i32 s73, s72, 31
	s_mul_i32 s74, s36, 37
	s_ashr_i32 s75, s74, 31
	s_mul_i32 s26, s36, 38
	s_ashr_i32 s27, s26, 31
	s_mul_i32 s84, s36, 39
	s_ashr_i32 s85, s84, 31
	s_mul_i32 s8, s36, 40
	s_ashr_i32 s9, s8, 31
	s_mul_i32 s94, s36, 41
	s_ashr_i32 s95, s94, 31
	s_mul_i32 s82, s36, 42
	s_ashr_i32 s83, s82, 31
	s_mul_i32 s86, s36, 43
	s_ashr_i32 s87, s86, 31
	s_mul_i32 s78, s36, 44
	s_ashr_i32 s79, s78, 31
	s_mul_i32 s80, s36, 45
	s_ashr_i32 s81, s80, 31
	s_mul_i32 s42, s36, 47
	s_ashr_i32 s43, s42, 31
	s_lshl_b64 s[20:21], s[20:21], 10
	v_and_b32_e32 v46, 31, v34
	v_bfe_u32 v79, v34, 4, 1
	v_and_b32_e32 v48, 15, v34
	v_or_b32_e32 v67, 32, v46
	v_lshrrev_b32_e32 v80, 4, v67
	global_load_ushort v102, v[4:5], off
	v_lshl_add_u64 v[4:5], v[30:31], 0, s[0:1]
	global_load_ushort v103, v[4:5], off
	s_lshl_b32 s0, s36, 2
	s_ashr_i32 s1, s0, 31
	v_writelane_b32 v255, s0, 4
	v_writelane_b32 v255, s1, 5
	s_lshl_b64 s[0:1], s[0:1], 9
	v_lshl_add_u64 v[4:5], v[30:31], 0, s[0:1]
	s_mul_i32 s0, s36, 5
	s_ashr_i32 s1, s0, 31
	v_writelane_b32 v255, s0, 6
	global_load_ushort v104, v[4:5], off
	s_nop 0
	v_writelane_b32 v255, s1, 7
	s_lshl_b64 s[0:1], s[0:1], 9
	v_lshl_add_u64 v[4:5], v[30:31], 0, s[0:1]
	global_load_ushort v105, v[4:5], off
	s_mul_i32 s0, s36, 6
	s_ashr_i32 s1, s0, 31
	v_writelane_b32 v255, s0, 8
	v_writelane_b32 v255, s1, 9
	s_lshl_b64 s[0:1], s[0:1], 9
	v_lshl_add_u64 v[6:7], v[30:31], 0, s[0:1]
	s_mul_i32 s0, s36, 7
	s_ashr_i32 s1, s0, 31
	v_writelane_b32 v255, s0, 10
	global_load_ushort v106, v[6:7], off
	s_nop 0
	v_writelane_b32 v255, s1, 11
	s_lshl_b64 s[0:1], s[0:1], 9
	v_lshl_add_u64 v[6:7], v[30:31], 0, s[0:1]
	global_load_ushort v107, v[6:7], off
	s_lshl_b32 s0, s36, 3
	s_ashr_i32 s1, s0, 31
	v_writelane_b32 v255, s0, 12
	v_writelane_b32 v255, s1, 13
	s_lshl_b64 s[0:1], s[0:1], 9
	v_lshl_add_u64 v[6:7], v[30:31], 0, s[0:1]
	s_mul_i32 s0, s36, 9
	s_ashr_i32 s1, s0, 31
	v_writelane_b32 v255, s0, 14
	global_load_ushort v108, v[6:7], off
	s_nop 0
	v_writelane_b32 v255, s1, 15
	s_lshl_b64 s[0:1], s[0:1], 9
	v_lshl_add_u64 v[6:7], v[30:31], 0, s[0:1]
	global_load_ushort v109, v[6:7], off
	s_mul_i32 s0, s36, 10
	s_ashr_i32 s1, s0, 31
	v_writelane_b32 v255, s0, 16
	v_writelane_b32 v255, s1, 17
	s_lshl_b64 s[0:1], s[0:1], 9
	v_lshl_add_u64 v[8:9], v[30:31], 0, s[0:1]
	s_mul_i32 s0, s36, 11
	s_ashr_i32 s1, s0, 31
	v_writelane_b32 v255, s0, 18
	global_load_ushort v110, v[8:9], off
	s_nop 0
	v_writelane_b32 v255, s1, 19
	s_lshl_b64 s[0:1], s[0:1], 9
	v_lshl_add_u64 v[8:9], v[30:31], 0, s[0:1]
	global_load_ushort v111, v[8:9], off
	s_mul_i32 s0, s36, 12
	s_ashr_i32 s1, s0, 31
	v_writelane_b32 v255, s0, 20
	v_writelane_b32 v255, s1, 21
	s_lshl_b64 s[0:1], s[0:1], 9
	v_lshl_add_u64 v[8:9], v[30:31], 0, s[0:1]
	s_mul_i32 s0, s36, 13
	s_ashr_i32 s1, s0, 31
	v_writelane_b32 v255, s0, 22
	global_load_ushort v112, v[8:9], off
	s_nop 0
	v_writelane_b32 v255, s1, 23
	s_lshl_b64 s[0:1], s[0:1], 9
	v_lshl_add_u64 v[8:9], v[30:31], 0, s[0:1]
	global_load_ushort v113, v[8:9], off
	s_mul_i32 s0, s36, 14
	s_ashr_i32 s1, s0, 31
	v_writelane_b32 v255, s0, 24
	v_writelane_b32 v255, s1, 25
	s_lshl_b64 s[0:1], s[0:1], 9
	v_lshl_add_u64 v[10:11], v[30:31], 0, s[0:1]
	s_lshl_b64 s[0:1], s[90:91], 9
	global_load_ushort v114, v[10:11], off
	v_lshl_add_u64 v[10:11], v[30:31], 0, s[0:1]
	global_load_ushort v115, v[10:11], off
	s_lshl_b32 s0, s36, 4
	s_ashr_i32 s1, s0, 31
	v_writelane_b32 v255, s0, 26
	v_writelane_b32 v255, s1, 27
	s_lshl_b64 s[0:1], s[0:1], 9
	v_lshl_add_u64 v[10:11], v[30:31], 0, s[0:1]
	s_mul_i32 s0, s36, 17
	s_ashr_i32 s1, s0, 31
	v_writelane_b32 v255, s0, 28
	global_load_ushort v116, v[10:11], off
	s_nop 0
	v_writelane_b32 v255, s1, 29
	s_lshl_b64 s[0:1], s[0:1], 9
	v_lshl_add_u64 v[10:11], v[30:31], 0, s[0:1]
	global_load_ushort v117, v[10:11], off
	s_mul_i32 s0, s36, 18
	s_ashr_i32 s1, s0, 31
	v_writelane_b32 v255, s0, 30
	v_writelane_b32 v255, s1, 31
	s_lshl_b64 s[0:1], s[0:1], 9
	v_lshl_add_u64 v[12:13], v[30:31], 0, s[0:1]
	s_mul_i32 s0, s36, 19
	s_ashr_i32 s1, s0, 31
	v_writelane_b32 v255, s0, 32
	global_load_ushort v118, v[12:13], off
	s_nop 0
	v_writelane_b32 v255, s1, 33
	s_lshl_b64 s[0:1], s[0:1], 9
	v_lshl_add_u64 v[12:13], v[30:31], 0, s[0:1]
	global_load_ushort v119, v[12:13], off
	s_mul_i32 s0, s36, 20
	s_ashr_i32 s1, s0, 31
	v_writelane_b32 v255, s0, 34
	v_writelane_b32 v255, s1, 35
	s_lshl_b64 s[0:1], s[0:1], 9
	v_lshl_add_u64 v[12:13], v[30:31], 0, s[0:1]
	s_lshl_b64 s[0:1], s[12:13], 9
	global_load_ushort v120, v[12:13], off
	v_lshl_add_u64 v[12:13], v[30:31], 0, s[0:1]
	global_load_ushort v121, v[12:13], off
	s_lshl_b64 s[0:1], s[34:35], 9
	v_lshl_add_u64 v[14:15], v[30:31], 0, s[0:1]
	s_lshl_b64 s[0:1], s[28:29], 9
	global_load_ushort v122, v[14:15], off
	v_lshl_add_u64 v[14:15], v[30:31], 0, s[0:1]
	global_load_ushort v123, v[14:15], off
	s_lshl_b64 s[0:1], s[14:15], 9
	v_lshl_add_u64 v[14:15], v[30:31], 0, s[0:1]
	s_lshl_b64 s[0:1], s[96:97], 9
	global_load_ushort v124, v[14:15], off
	v_lshl_add_u64 v[14:15], v[30:31], 0, s[0:1]
	global_load_ushort v125, v[14:15], off
	s_lshl_b64 s[0:1], s[52:53], 9
	v_lshl_add_u64 v[16:17], v[30:31], 0, s[0:1]
	s_lshl_b64 s[0:1], s[16:17], 9
	global_load_ushort v126, v[16:17], off
	v_lshl_add_u64 v[16:17], v[30:31], 0, s[0:1]
	global_load_ushort v127, v[16:17], off
	s_lshl_b64 s[0:1], s[4:5], 9
	v_lshl_add_u64 v[16:17], v[30:31], 0, s[0:1]
	s_lshl_b64 s[0:1], s[92:93], 9
	global_load_ushort v128, v[16:17], off
	v_lshl_add_u64 v[16:17], v[30:31], 0, s[0:1]
	global_load_ushort v129, v[16:17], off
	s_lshl_b64 s[0:1], s[38:39], 9
	v_lshl_add_u64 v[18:19], v[30:31], 0, s[0:1]
	s_lshl_b64 s[0:1], s[18:19], 9
	global_load_ushort v130, v[18:19], off
	v_lshl_add_u64 v[18:19], v[30:31], 0, s[0:1]
	global_load_ushort v131, v[18:19], off
	s_lshl_b64 s[0:1], s[22:23], 9
	v_lshl_add_u64 v[18:19], v[30:31], 0, s[0:1]
	s_lshl_b64 s[0:1], s[24:25], 9
	global_load_ushort v132, v[18:19], off
	v_lshl_add_u64 v[18:19], v[30:31], 0, s[0:1]
	global_load_ushort v133, v[18:19], off
	s_lshl_b64 s[0:1], s[30:31], 9
	v_lshl_add_u64 v[20:21], v[30:31], 0, s[0:1]
	s_lshl_b64 s[0:1], s[6:7], 9
	global_load_ushort v134, v[20:21], off
	v_lshl_add_u64 v[20:21], v[30:31], 0, s[0:1]
	global_load_ushort v135, v[20:21], off
	s_lshl_b64 s[0:1], s[72:73], 9
	v_lshl_add_u64 v[20:21], v[30:31], 0, s[0:1]
	s_lshl_b64 s[0:1], s[74:75], 9
	global_load_ushort v136, v[20:21], off
	v_lshl_add_u64 v[20:21], v[30:31], 0, s[0:1]
	global_load_ushort v137, v[20:21], off
	s_lshl_b64 s[0:1], s[26:27], 9
	v_lshl_add_u64 v[22:23], v[30:31], 0, s[0:1]
	s_lshl_b64 s[0:1], s[84:85], 9
	global_load_ushort v138, v[22:23], off
	v_lshl_add_u64 v[22:23], v[30:31], 0, s[0:1]
	global_load_ushort v139, v[22:23], off
	s_lshl_b64 s[0:1], s[8:9], 9
	v_lshl_add_u64 v[22:23], v[30:31], 0, s[0:1]
	s_lshl_b64 s[0:1], s[94:95], 9
	global_load_ushort v140, v[22:23], off
	v_lshl_add_u64 v[22:23], v[30:31], 0, s[0:1]
	global_load_ushort v141, v[22:23], off
	s_lshl_b64 s[0:1], s[82:83], 9
	v_lshl_add_u64 v[24:25], v[30:31], 0, s[0:1]
	s_lshl_b64 s[0:1], s[86:87], 9
	global_load_ushort v142, v[24:25], off
	v_lshl_add_u64 v[24:25], v[30:31], 0, s[0:1]
	global_load_ushort v143, v[24:25], off
	s_lshl_b64 s[0:1], s[78:79], 9
	v_lshl_add_u64 v[24:25], v[30:31], 0, s[0:1]
	s_lshl_b64 s[0:1], s[80:81], 9
	global_load_ushort v144, v[24:25], off
	v_lshl_add_u64 v[24:25], v[30:31], 0, s[0:1]
	global_load_ushort v145, v[24:25], off
	s_mul_i32 s0, s36, 46
	s_ashr_i32 s1, s0, 31
	s_lshl_b64 s[10:11], s[0:1], 9
	v_lshl_add_u64 v[26:27], v[30:31], 0, s[10:11]
	s_lshl_b64 s[10:11], s[42:43], 9
	global_load_ushort v146, v[26:27], off
	v_lshl_add_u64 v[26:27], v[30:31], 0, s[10:11]
	global_load_ushort v147, v[26:27], off
	s_mul_i32 s10, s36, 48
	s_ashr_i32 s11, s10, 31
	s_lshl_b64 s[40:41], s[10:11], 9
	v_lshl_add_u64 v[26:27], v[30:31], 0, s[40:41]
	s_mul_i32 s40, s36, 49
	s_ashr_i32 s41, s40, 31
	s_lshl_b64 s[44:45], s[40:41], 9
	global_load_ushort v148, v[26:27], off
	v_lshl_add_u64 v[26:27], v[30:31], 0, s[44:45]
	global_load_ushort v149, v[26:27], off
	s_mul_i32 s44, s36, 50
	s_ashr_i32 s45, s44, 31
	s_lshl_b64 s[46:47], s[44:45], 9
	v_lshl_add_u64 v[28:29], v[30:31], 0, s[46:47]
	s_mul_i32 s46, s36, 51
	s_ashr_i32 s47, s46, 31
	s_lshl_b64 s[48:49], s[46:47], 9
	global_load_ushort v150, v[28:29], off
	v_lshl_add_u64 v[28:29], v[30:31], 0, s[48:49]
	global_load_ushort v151, v[28:29], off
	s_mul_i32 s48, s36, 52
	s_ashr_i32 s49, s48, 31
	s_lshl_b64 s[50:51], s[48:49], 9
	v_lshl_add_u64 v[28:29], v[30:31], 0, s[50:51]
	s_mul_i32 s50, s36, 53
	s_ashr_i32 s51, s50, 31
	s_lshl_b64 s[54:55], s[50:51], 9
	global_load_ushort v152, v[28:29], off
	v_lshl_add_u64 v[28:29], v[30:31], 0, s[54:55]
	global_load_ushort v153, v[28:29], off
	s_mul_i32 s54, s36, 54
	s_ashr_i32 s55, s54, 31
	s_lshl_b64 s[56:57], s[54:55], 9
	v_lshl_add_u64 v[32:33], v[30:31], 0, s[56:57]
	s_mul_i32 s56, s36, 55
	s_ashr_i32 s57, s56, 31
	s_lshl_b64 s[58:59], s[56:57], 9
	global_load_ushort v154, v[32:33], off
	v_lshl_add_u64 v[32:33], v[30:31], 0, s[58:59]
	global_load_ushort v155, v[32:33], off
	s_mul_i32 s58, s36, 56
	s_ashr_i32 s59, s58, 31
	s_lshl_b64 s[60:61], s[58:59], 9
	v_lshl_add_u64 v[32:33], v[30:31], 0, s[60:61]
	s_mul_i32 s60, s36, 57
	s_ashr_i32 s61, s60, 31
	s_lshl_b64 s[62:63], s[60:61], 9
	global_load_ushort v156, v[32:33], off
	v_lshl_add_u64 v[32:33], v[30:31], 0, s[62:63]
	global_load_ushort v157, v[32:33], off
	s_mul_i32 s62, s36, 58
	s_ashr_i32 s63, s62, 31
	s_lshl_b64 s[64:65], s[62:63], 9
	v_lshl_add_u64 v[32:33], v[30:31], 0, s[64:65]
	s_mul_i32 s64, s36, 59
	s_ashr_i32 s65, s64, 31
	s_lshl_b64 s[66:67], s[64:65], 9
	global_load_ushort v158, v[32:33], off
	v_lshl_add_u64 v[32:33], v[30:31], 0, s[66:67]
	global_load_ushort v159, v[32:33], off
	s_mul_i32 s66, s36, 60
	s_ashr_i32 s67, s66, 31
	s_lshl_b64 s[68:69], s[66:67], 9
	v_lshl_add_u64 v[32:33], v[30:31], 0, s[68:69]
	s_mul_i32 s68, s36, 61
	s_ashr_i32 s69, s68, 31
	s_lshl_b64 s[70:71], s[68:69], 9
	global_load_ushort v160, v[32:33], off
	v_lshl_add_u64 v[32:33], v[30:31], 0, s[70:71]
	global_load_ushort v161, v[32:33], off
	s_mul_i32 s70, s36, 62
	s_ashr_i32 s71, s70, 31
	s_lshl_b64 s[76:77], s[70:71], 9
	v_lshl_add_u64 v[32:33], v[30:31], 0, s[76:77]
	s_mul_i32 s76, s36, 63
	s_ashr_i32 s77, s76, 31
	s_lshl_b64 vcc, s[76:77], 9
	v_lshl_add_u64 v[30:31], v[30:31], 0, vcc
	global_load_ushort v162, v[32:33], off
	s_movk_i32 vcc_lo, 0x90
	global_load_ushort v163, v[30:31], off
	s_add_u32 s20, s88, s20
	s_addc_u32 s21, s89, s21
	s_lshl_b32 s3, s3, 2
	s_add_u32 s20, s20, s3
	s_addc_u32 s21, s21, 0
	s_lshl_b64 s[6:7], s[6:7], 10
	s_lshl_b64 s[0:1], s[0:1], 10
	s_ashr_i32 s3, s2, 31
	s_waitcnt vmcnt(0)
	v_lshl_or_b32 v2, v101, 16, v100
	v_lshl_or_b32 v3, v103, 16, v102
	v_lshl_or_b32 v4, v105, 16, v104
	v_lshl_or_b32 v5, v107, 16, v106
	v_lshl_or_b32 v6, v109, 16, v108
	v_lshl_or_b32 v7, v111, 16, v110
	v_lshl_or_b32 v8, v113, 16, v112
	v_lshl_or_b32 v9, v115, 16, v114
	v_lshl_or_b32 v10, v117, 16, v116
	v_lshl_or_b32 v11, v119, 16, v118
	v_lshl_or_b32 v12, v121, 16, v120
	v_lshl_or_b32 v13, v123, 16, v122
	v_lshl_or_b32 v14, v125, 16, v124
	v_lshl_or_b32 v15, v127, 16, v126
	v_lshl_or_b32 v16, v129, 16, v128
	v_lshl_or_b32 v17, v131, 16, v130
	v_lshl_or_b32 v18, v133, 16, v132
	v_lshl_or_b32 v19, v135, 16, v134
	v_lshl_or_b32 v20, v137, 16, v136
	v_lshl_or_b32 v21, v139, 16, v138
	v_lshl_or_b32 v22, v141, 16, v140
	v_lshl_or_b32 v23, v143, 16, v142
	v_lshl_or_b32 v24, v145, 16, v144
	v_lshl_or_b32 v25, v147, 16, v146
	v_lshl_or_b32 v26, v149, 16, v148
	v_lshl_or_b32 v27, v151, 16, v150
	v_lshl_or_b32 v28, v153, 16, v152
	v_lshl_or_b32 v29, v155, 16, v154
	v_lshl_or_b32 v36, v157, 16, v156
	v_lshl_or_b32 v37, v159, 16, v158
	v_lshl_or_b32 v38, v161, 16, v160
	v_lshl_or_b32 v39, v163, 16, v162
	v_mul_lo_u32 v0, v34, vcc_lo
	v_readlane_b32 vcc_lo, v254, 58
	s_nop 1
	v_add_u32_e32 v0, vcc_lo, v0
	ds_write_b128 v0, v[2:5] offset:9216
	ds_write_b128 v0, v[6:9] offset:9232
	ds_write_b128 v0, v[10:13] offset:9248
	ds_write_b128 v0, v[14:17] offset:9264
	ds_write_b128 v0, v[18:21] offset:9280
	ds_write_b128 v0, v[22:25] offset:9296
	ds_write_b128 v0, v[26:29] offset:9312
	ds_write_b128 v0, v[36:39] offset:9328
	v_lshlrev_b64 v[2:3], 2, v[34:35]
	v_lshl_add_u64 v[6:7], s[20:21], 0, v[2:3]
	s_lshl_b64 s[20:21], s[22:23], 10
	v_lshl_add_u64 v[4:5], v[6:7], 0, s[20:21]
	s_lshl_b64 s[20:21], s[24:25], 10
	v_lshl_add_u64 v[8:9], v[6:7], 0, s[20:21]
	s_lshl_b64 s[20:21], s[30:31], 10
	global_load_dword v4, v[4:5], off
	v_lshl_add_u64 v[10:11], v[6:7], 0, s[6:7]
	global_load_dword v5, v[8:9], off
	v_lshl_add_u64 v[8:9], v[6:7], 0, s[20:21]
	s_lshl_b64 s[6:7], s[72:73], 10
	global_load_dword v8, v[8:9], off
	s_mov_b32 s72, 0xa000
	global_load_dword v9, v[10:11], off
	v_lshl_add_u64 v[10:11], v[6:7], 0, s[6:7]
	s_lshl_b64 s[6:7], s[74:75], 10
	v_lshl_add_u64 v[12:13], v[6:7], 0, s[6:7]
	s_lshl_b64 s[6:7], s[26:27], 10
	global_load_dword v10, v[10:11], off
	s_mov_b32 s73, 0x1e000
	global_load_dword v11, v[12:13], off
	v_lshl_add_u64 v[12:13], v[6:7], 0, s[6:7]
	s_lshl_b64 s[6:7], s[84:85], 10
	v_lshl_add_u64 v[14:15], v[6:7], 0, s[6:7]
	s_lshl_b64 s[6:7], s[8:9], 10
	global_load_dword v12, v[12:13], off
	v_readlane_b32 s84, v253, 61
	global_load_dword v13, v[14:15], off
	v_lshl_add_u64 v[14:15], v[6:7], 0, s[6:7]
	s_lshl_b64 s[6:7], s[94:95], 10
	v_lshl_add_u64 v[16:17], v[6:7], 0, s[6:7]
	s_lshl_b64 s[6:7], s[82:83], 10
	global_load_dword v14, v[14:15], off
	v_readlane_b32 s82, v253, 58
	global_load_dword v15, v[16:17], off
	v_lshl_add_u64 v[16:17], v[6:7], 0, s[6:7]
	s_lshl_b64 s[6:7], s[86:87], 10
	v_lshl_add_u64 v[18:19], v[6:7], 0, s[6:7]
	s_lshl_b64 s[6:7], s[78:79], 10
	global_load_dword v16, v[16:17], off
	v_readlane_b32 s78, v253, 55
	global_load_dword v17, v[18:19], off
	v_lshl_add_u64 v[18:19], v[6:7], 0, s[6:7]
	s_lshl_b64 s[6:7], s[80:81], 10
	v_lshl_add_u64 v[20:21], v[6:7], 0, s[6:7]
	global_load_dword v18, v[18:19], off
	v_readlane_b32 s7, v254, 54
	global_load_dword v19, v[20:21], off
	v_lshl_add_u64 v[20:21], v[6:7], 0, s[0:1]
	s_lshl_b64 s[0:1], s[42:43], 10
	v_lshl_add_u64 v[22:23], v[6:7], 0, s[0:1]
	s_lshl_b64 s[0:1], s[10:11], 10
	global_load_dword v20, v[20:21], off
	v_readlane_b32 s80, v253, 56
	global_load_dword v21, v[22:23], off
	v_lshl_add_u64 v[22:23], v[6:7], 0, s[0:1]
	s_lshl_b64 s[0:1], s[40:41], 10
	v_lshl_add_u64 v[24:25], v[6:7], 0, s[0:1]
	s_lshl_b64 s[0:1], s[44:45], 10
	global_load_dword v22, v[22:23], off
	v_readlane_b32 s81, v253, 57
	global_load_dword v23, v[24:25], off
	v_lshl_add_u64 v[24:25], v[6:7], 0, s[0:1]
	s_lshl_b64 s[0:1], s[46:47], 10
	v_lshl_add_u64 v[26:27], v[6:7], 0, s[0:1]
	s_lshl_b64 s[0:1], s[48:49], 10
	global_load_dword v24, v[24:25], off
	v_readlane_b32 s42, v254, 31
	global_load_dword v25, v[26:27], off
	v_lshl_add_u64 v[26:27], v[6:7], 0, s[0:1]
	s_lshl_b64 s[0:1], s[50:51], 10
	v_lshl_add_u64 v[28:29], v[6:7], 0, s[0:1]
	s_lshl_b64 s[0:1], s[54:55], 10
	global_load_dword v26, v[26:27], off
	v_readlane_b32 s54, v254, 12
	global_load_dword v27, v[28:29], off
	v_lshl_add_u64 v[28:29], v[6:7], 0, s[0:1]
	s_lshl_b64 s[0:1], s[56:57], 10
	v_lshl_add_u64 v[30:31], v[6:7], 0, s[0:1]
	s_lshl_b64 s[0:1], s[58:59], 10
	global_load_dword v28, v[28:29], off
	v_readlane_b32 s83, v253, 59
	global_load_dword v29, v[30:31], off
	v_lshl_add_u64 v[30:31], v[6:7], 0, s[0:1]
	s_lshl_b64 s[0:1], s[60:61], 10
	v_lshl_add_u64 v[32:33], v[6:7], 0, s[0:1]
	s_lshl_b64 s[0:1], s[62:63], 10
	global_load_dword v30, v[30:31], off
	v_readlane_b32 s79, v253, 60
	global_load_dword v31, v[32:33], off
	v_lshl_add_u64 v[32:33], v[6:7], 0, s[0:1]
	s_lshl_b64 s[0:1], s[64:65], 10
	v_lshl_add_u64 v[36:37], v[6:7], 0, s[0:1]
	s_lshl_b64 s[0:1], s[66:67], 10
	global_load_dword v32, v[32:33], off
	v_readlane_b32 s85, v253, 62
	global_load_dword v33, v[36:37], off
	v_lshl_add_u64 v[36:37], v[6:7], 0, s[0:1]
	s_lshl_b64 s[0:1], s[68:69], 10
	v_lshl_add_u64 v[38:39], v[6:7], 0, s[0:1]
	s_lshl_b64 s[0:1], s[70:71], 10
	global_load_dword v36, v[36:37], off
	v_readlane_b32 s86, v253, 63
	global_load_dword v37, v[38:39], off
	v_lshl_add_u64 v[38:39], v[6:7], 0, s[0:1]
	s_lshl_b64 s[0:1], s[76:77], 10
	global_load_dword v35, v[38:39], off
	v_lshl_add_u64 v[38:39], v[6:7], 0, s[0:1]
	global_load_dword v38, v[38:39], off
	s_lshl_b64 s[0:1], s[36:37], 10
	v_readlane_b32 s36, v254, 56
	v_readlane_b32 s37, v254, 57
	s_movk_i32 s81, 0x4000
	s_movk_i32 s87, 0x3000
	s_mov_b32 s94, 0x10000
	s_movk_i32 s95, 0x6000
	s_mov_b32 s74, 0xc000
	s_mov_b32 s75, 0xe000
	s_mov_b32 s10, 0xca01000
	s_mov_b32 s11, 0xeb01000
	s_mov_b32 s77, 0x42000
	s_mov_b32 s20, 0x4a000
	s_mov_b32 s21, 0x52000
	s_mov_b32 s76, 0x5a000
	s_mov_b32 s24, 0x63000
	s_mov_b32 s31, 0xa5000
	s_movk_i32 s46, 0xffd0
	s_movk_i32 s50, 0xffc0
	s_mov_b32 s51, 0x41000000
	s_mov_b64 s[48:49], 0xca00100
	v_readlane_b32 s43, v254, 32
	v_readlane_b32 s55, v254, 13
	s_waitcnt vmcnt(2)
	v_pk_add_f32 v[40:41], v[36:37], 1.0 op_sel_hi:[1,0] neg_lo:[1,0] neg_hi:[1,0]
	s_waitcnt vmcnt(1)
	v_sub_f32_e32 v39, 1.0, v35
	s_waitcnt vmcnt(0)
	v_mul_f32_e32 v45, v38, v39
	v_mul_f32_e32 v39, v35, v38
	v_sub_f32_e32 v44, 1.0, v38
	v_mul_f32_e32 v38, v37, v39
	v_mul_f32_e32 v37, v36, v38
	v_mul_f32_e32 v36, v33, v37
	v_pk_mul_f32 v[40:41], v[40:41], v[38:39]
	v_pk_add_f32 v[38:39], v[32:33], 1.0 op_sel_hi:[1,0] neg_lo:[1,0] neg_hi:[1,0]
	v_mul_f32_e32 v33, v32, v36
	v_mul_f32_e32 v32, v31, v33
	v_pk_mul_f32 v[38:39], v[38:39], v[36:37]
	v_pk_add_f32 v[36:37], v[30:31], 1.0 op_sel_hi:[1,0] neg_lo:[1,0] neg_hi:[1,0]
	v_mul_f32_e32 v31, v30, v32
	v_mul_f32_e32 v30, v29, v31
	v_pk_mul_f32 v[36:37], v[36:37], v[32:33]
	v_pk_add_f32 v[32:33], v[28:29], 1.0 op_sel_hi:[1,0] neg_lo:[1,0] neg_hi:[1,0]
	v_mul_f32_e32 v29, v28, v30
	v_mul_f32_e32 v28, v27, v29
	v_pk_mul_f32 v[32:33], v[32:33], v[30:31]
	v_pk_add_f32 v[30:31], v[26:27], 1.0 op_sel_hi:[1,0] neg_lo:[1,0] neg_hi:[1,0]
	v_mul_f32_e32 v27, v26, v28
	v_mul_f32_e32 v26, v25, v27
	v_pk_mul_f32 v[30:31], v[30:31], v[28:29]
	v_pk_add_f32 v[28:29], v[24:25], 1.0 op_sel_hi:[1,0] neg_lo:[1,0] neg_hi:[1,0]
	v_mul_f32_e32 v25, v24, v26
	v_mul_f32_e32 v24, v23, v25
	v_pk_mul_f32 v[28:29], v[28:29], v[26:27]
	v_pk_add_f32 v[26:27], v[22:23], 1.0 op_sel_hi:[1,0] neg_lo:[1,0] neg_hi:[1,0]
	v_mul_f32_e32 v23, v22, v24
	v_mul_f32_e32 v22, v21, v23
	v_pk_mul_f32 v[26:27], v[26:27], v[24:25]
	v_pk_add_f32 v[24:25], v[20:21], 1.0 op_sel_hi:[1,0] neg_lo:[1,0] neg_hi:[1,0]
	v_mul_f32_e32 v21, v20, v22
	v_mul_f32_e32 v20, v19, v21
	v_pk_mul_f32 v[24:25], v[24:25], v[22:23]
	v_pk_add_f32 v[22:23], v[18:19], 1.0 op_sel_hi:[1,0] neg_lo:[1,0] neg_hi:[1,0]
	v_mul_f32_e32 v19, v18, v20
	v_mul_f32_e32 v18, v17, v19
	v_pk_mul_f32 v[22:23], v[22:23], v[20:21]
	v_pk_add_f32 v[20:21], v[16:17], 1.0 op_sel_hi:[1,0] neg_lo:[1,0] neg_hi:[1,0]
	v_mul_f32_e32 v17, v16, v18
	v_mul_f32_e32 v16, v15, v17
	v_pk_mul_f32 v[20:21], v[20:21], v[18:19]
	v_pk_add_f32 v[18:19], v[14:15], 1.0 op_sel_hi:[1,0] neg_lo:[1,0] neg_hi:[1,0]
	v_mul_f32_e32 v15, v14, v16
	v_mul_f32_e32 v14, v13, v15
	v_pk_mul_f32 v[18:19], v[18:19], v[16:17]
	v_pk_add_f32 v[16:17], v[12:13], 1.0 op_sel_hi:[1,0] neg_lo:[1,0] neg_hi:[1,0]
	v_mul_f32_e32 v13, v12, v14
	v_mul_f32_e32 v12, v11, v13
	v_pk_mul_f32 v[42:43], v[16:17], v[14:15]
	v_pk_add_f32 v[14:15], v[10:11], 1.0 op_sel_hi:[1,0] neg_lo:[1,0] neg_hi:[1,0]
	v_mul_f32_e32 v11, v10, v12
	v_mul_f32_e32 v10, v9, v11
	v_mul_f32_e32 v17, v8, v10
	v_pk_mul_f32 v[14:15], v[14:15], v[12:13]
	v_pk_add_f32 v[12:13], v[8:9], 1.0 op_sel_hi:[1,0] neg_lo:[1,0] neg_hi:[1,0]
	v_mul_f32_e32 v16, v5, v17
	v_pk_add_f32 v[8:9], v[4:5], 1.0 op_sel_hi:[1,0] neg_lo:[1,0] neg_hi:[1,0]
	v_pk_mul_f32 v[12:13], v[12:13], v[10:11]
	v_pk_mul_f32 v[8:9], v[8:9], v[16:17]
	v_cvt_pk_bf16_f32 v10, v14, v15
	v_cvt_pk_bf16_f32 v8, v8, v9
	v_cvt_pk_bf16_f32 v9, v12, v13
	v_cvt_pk_bf16_f32 v11, v42, v43
	ds_write_b128 v0, v[8:11] offset:64
	v_cvt_pk_bf16_f32 v8, v18, v19
	v_cvt_pk_bf16_f32 v9, v20, v21
	v_cvt_pk_bf16_f32 v10, v22, v23
	v_cvt_pk_bf16_f32 v11, v24, v25
	ds_write_b128 v0, v[8:11] offset:80
	v_cvt_pk_bf16_f32 v8, v26, v27
	v_cvt_pk_bf16_f32 v9, v28, v29
	v_cvt_pk_bf16_f32 v10, v30, v31
	v_cvt_pk_bf16_f32 v11, v32, v33
	ds_write_b128 v0, v[8:11] offset:96
	v_cvt_pk_bf16_f32 v8, v36, v37
	v_cvt_pk_bf16_f32 v9, v38, v39
	v_cvt_pk_bf16_f32 v10, v40, v41
	v_cvt_pk_bf16_f32 v11, v45, v44
	ds_write_b128 v0, v[8:11] offset:112
	v_lshl_add_u64 v[10:11], v[6:7], 0, s[0:1]
	v_readlane_b32 s0, v255, 0
	v_readlane_b32 s1, v255, 1
	s_lshl_b64 s[0:1], s[0:1], 10
	global_load_dword v8, v[6:7], off
	global_load_dword v9, v[10:11], off
	v_lshl_add_u64 v[10:11], v[6:7], 0, s[0:1]
	v_readlane_b32 s0, v255, 2
	v_readlane_b32 s1, v255, 3
	s_lshl_b64 s[0:1], s[0:1], 10
	global_load_dword v10, v[10:11], off
	v_lshl_add_u64 v[12:13], v[6:7], 0, s[0:1]
	v_readlane_b32 s0, v255, 4
	v_readlane_b32 s1, v255, 5
	s_lshl_b64 s[0:1], s[0:1], 10
	global_load_dword v11, v[12:13], off
	v_lshl_add_u64 v[12:13], v[6:7], 0, s[0:1]
	v_readlane_b32 s0, v255, 6
	v_readlane_b32 s1, v255, 7
	s_lshl_b64 s[0:1], s[0:1], 10
	global_load_dword v12, v[12:13], off
	v_lshl_add_u64 v[14:15], v[6:7], 0, s[0:1]
	v_readlane_b32 s0, v255, 8
	v_readlane_b32 s1, v255, 9
	s_lshl_b64 s[0:1], s[0:1], 10
	global_load_dword v13, v[14:15], off
	v_lshl_add_u64 v[14:15], v[6:7], 0, s[0:1]
	v_readlane_b32 s0, v255, 10
	v_readlane_b32 s1, v255, 11
	s_lshl_b64 s[0:1], s[0:1], 10
	global_load_dword v14, v[14:15], off
	v_lshl_add_u64 v[18:19], v[6:7], 0, s[0:1]
	v_readlane_b32 s0, v255, 12
	v_readlane_b32 s1, v255, 13
	s_lshl_b64 s[0:1], s[0:1], 10
	global_load_dword v15, v[18:19], off
	v_lshl_add_u64 v[18:19], v[6:7], 0, s[0:1]
	v_readlane_b32 s0, v255, 14
	v_readlane_b32 s1, v255, 15
	s_lshl_b64 s[0:1], s[0:1], 10
	global_load_dword v18, v[18:19], off
	v_lshl_add_u64 v[20:21], v[6:7], 0, s[0:1]
	v_readlane_b32 s0, v255, 16
	v_readlane_b32 s1, v255, 17
	s_lshl_b64 s[0:1], s[0:1], 10
	global_load_dword v19, v[20:21], off
	v_lshl_add_u64 v[20:21], v[6:7], 0, s[0:1]
	v_readlane_b32 s0, v255, 18
	v_readlane_b32 s1, v255, 19
	s_lshl_b64 s[0:1], s[0:1], 10
	global_load_dword v20, v[20:21], off
	v_lshl_add_u64 v[22:23], v[6:7], 0, s[0:1]
	v_readlane_b32 s0, v255, 20
	v_readlane_b32 s1, v255, 21
	s_lshl_b64 s[0:1], s[0:1], 10
	global_load_dword v21, v[22:23], off
	v_lshl_add_u64 v[22:23], v[6:7], 0, s[0:1]
	v_readlane_b32 s0, v255, 22
	v_readlane_b32 s1, v255, 23
	s_lshl_b64 s[0:1], s[0:1], 10
	global_load_dword v22, v[22:23], off
	v_lshl_add_u64 v[24:25], v[6:7], 0, s[0:1]
	v_readlane_b32 s0, v255, 24
	v_readlane_b32 s1, v255, 25
	s_lshl_b64 s[0:1], s[0:1], 10
	global_load_dword v23, v[24:25], off
	v_lshl_add_u64 v[24:25], v[6:7], 0, s[0:1]
	s_lshl_b64 s[0:1], s[90:91], 10
	v_lshl_add_u64 v[26:27], v[6:7], 0, s[0:1]
	v_readlane_b32 s0, v255, 26
	v_readlane_b32 s1, v255, 27
	s_lshl_b64 s[0:1], s[0:1], 10
	global_load_dword v24, v[24:25], off
	v_mul_f32_e32 v5, v4, v16
	global_load_dword v25, v[26:27], off
	v_lshl_add_u64 v[26:27], v[6:7], 0, s[0:1]
	v_readlane_b32 s0, v255, 28
	v_readlane_b32 s1, v255, 29
	s_lshl_b64 s[0:1], s[0:1], 10
	global_load_dword v26, v[26:27], off
	v_lshl_add_u64 v[28:29], v[6:7], 0, s[0:1]
	v_readlane_b32 s0, v255, 30
	v_readlane_b32 s1, v255, 31
	s_lshl_b64 s[0:1], s[0:1], 10
	global_load_dword v27, v[28:29], off
	v_lshl_add_u64 v[28:29], v[6:7], 0, s[0:1]
	v_readlane_b32 s0, v255, 32
	v_readlane_b32 s1, v255, 33
	s_lshl_b64 s[0:1], s[0:1], 10
	global_load_dword v28, v[28:29], off
	v_lshl_add_u64 v[30:31], v[6:7], 0, s[0:1]
	v_readlane_b32 s0, v255, 34
	v_readlane_b32 s1, v255, 35
	s_lshl_b64 s[0:1], s[0:1], 10
	global_load_dword v29, v[30:31], off
	v_lshl_add_u64 v[30:31], v[6:7], 0, s[0:1]
	s_lshl_b64 s[0:1], s[12:13], 10
	v_lshl_add_u64 v[32:33], v[6:7], 0, s[0:1]
	s_lshl_b64 s[0:1], s[34:35], 10
	global_load_dword v30, v[30:31], off
	s_movk_i32 s90, 0x1800
	global_load_dword v31, v[32:33], off
	v_lshl_add_u64 v[32:33], v[6:7], 0, s[0:1]
	s_lshl_b64 s[0:1], s[28:29], 10
	v_lshl_add_u64 v[36:37], v[6:7], 0, s[0:1]
	s_lshl_b64 s[0:1], s[14:15], 10
	global_load_dword v32, v[32:33], off
	s_movk_i32 s14, 0x90
	global_load_dword v33, v[36:37], off
	v_lshl_add_u64 v[36:37], v[6:7], 0, s[0:1]
	s_lshl_b64 s[0:1], s[96:97], 10
	v_lshl_add_u64 v[38:39], v[6:7], 0, s[0:1]
	s_lshl_b64 s[0:1], s[52:53], 10
	global_load_dword v36, v[36:37], off
	s_mov_b32 s91, 0x12000
	global_load_dword v37, v[38:39], off
	v_lshl_add_u64 v[38:39], v[6:7], 0, s[0:1]
	s_lshl_b64 s[0:1], s[16:17], 10
	v_lshl_add_u64 v[40:41], v[6:7], 0, s[0:1]
	s_lshl_b64 s[0:1], s[4:5], 10
	global_load_dword v38, v[38:39], off
	v_readlane_b32 s4, v254, 63
	global_load_dword v39, v[40:41], off
	v_lshl_add_u64 v[40:41], v[6:7], 0, s[0:1]
	s_lshl_b64 s[0:1], s[92:93], 10
	v_lshl_add_u64 v[42:43], v[6:7], 0, s[0:1]
	s_lshl_b64 s[0:1], s[38:39], 10
	global_load_dword v40, v[40:41], off
	s_movk_i32 s92, 0x5000
	global_load_dword v41, v[42:43], off
	v_lshl_add_u64 v[42:43], v[6:7], 0, s[0:1]
	s_lshl_b64 s[0:1], s[18:19], 10
	v_lshl_add_u64 v[6:7], v[6:7], 0, s[0:1]
	global_load_dword v42, v[42:43], off
	s_lshl_b64 s[0:1], s[2:3], 8
	global_load_dword v43, v[6:7], off
	v_readlane_b32 s3, v254, 59
	s_add_u32 s0, s3, s0
	v_readlane_b32 s3, v254, 60
	s_addc_u32 s1, s3, s1
	v_lshl_add_u64 v[2:3], s[0:1], 0, v[2:3]
	v_readlane_b32 s0, v254, 52
	s_ashr_i32 s3, s0, 31
	s_mul_hi_i32 s1, s33, 0x2100
	s_add_u32 s0, s4, s0
	s_addc_u32 s1, s1, s3
	s_lshl_b64 s[0:1], s[0:1], 8
	s_add_u32 s0, s36, s0
	s_addc_u32 s1, s37, s1
	s_movk_i32 s93, 0x2000
	s_mov_b32 s96, 0x18000
	s_mov_b32 s97, 0x8000
	s_movk_i32 s15, 0x1000
	s_mov_b32 s16, 0x21000
	s_mov_b32 s17, 0x29000
	s_mov_b32 s18, 0x31000
	s_mov_b32 s19, 0x39000
	s_mov_b32 s33, 0xad000
	s_mov_b32 s34, 0xb5000
	s_mov_b32 s35, 0xbd000
	s_mov_b32 s38, 0xc6000
	s_mov_b32 s39, 0xce000
	s_mov_b32 s52, 0xd6000
	s_mov_b32 s53, 0xde000
	s_waitcnt vmcnt(0)
	v_mul_f32_e32 v4, v5, v43
	v_pk_add_f32 v[6:7], v[42:43], 1.0 op_sel_hi:[1,0] neg_lo:[1,0] neg_hi:[1,0]
	s_nop 0
	v_pk_mul_f32 v[16:17], v[6:7], v[4:5]
	v_mul_f32_e32 v5, v42, v4
	v_mul_f32_e32 v4, v41, v5
	v_pk_add_f32 v[6:7], v[40:41], 1.0 op_sel_hi:[1,0] neg_lo:[1,0] neg_hi:[1,0]
	s_nop 0
	v_pk_mul_f32 v[42:43], v[6:7], v[4:5]
	v_mul_f32_e32 v5, v40, v4
	v_mul_f32_e32 v4, v39, v5
	v_pk_add_f32 v[6:7], v[38:39], 1.0 op_sel_hi:[1,0] neg_lo:[1,0] neg_hi:[1,0]
	s_nop 0
	v_pk_mul_f32 v[40:41], v[6:7], v[4:5]
	v_mul_f32_e32 v5, v38, v4
	v_mul_f32_e32 v4, v37, v5
	v_pk_add_f32 v[6:7], v[36:37], 1.0 op_sel_hi:[1,0] neg_lo:[1,0] neg_hi:[1,0]
	s_nop 0
	v_pk_mul_f32 v[38:39], v[6:7], v[4:5]
	v_mul_f32_e32 v5, v36, v4
	v_mul_f32_e32 v4, v33, v5
	v_pk_add_f32 v[6:7], v[32:33], 1.0 op_sel_hi:[1,0] neg_lo:[1,0] neg_hi:[1,0]
	s_nop 0
	v_pk_mul_f32 v[36:37], v[6:7], v[4:5]
	v_mul_f32_e32 v5, v32, v4
	v_mul_f32_e32 v4, v31, v5
	v_pk_add_f32 v[6:7], v[30:31], 1.0 op_sel_hi:[1,0] neg_lo:[1,0] neg_hi:[1,0]
	s_nop 0
	v_pk_mul_f32 v[32:33], v[6:7], v[4:5]
	v_mul_f32_e32 v5, v30, v4
	v_mul_f32_e32 v4, v29, v5
	v_pk_add_f32 v[6:7], v[28:29], 1.0 op_sel_hi:[1,0] neg_lo:[1,0] neg_hi:[1,0]
	s_nop 0
	v_pk_mul_f32 v[30:31], v[6:7], v[4:5]
	v_mul_f32_e32 v5, v28, v4
	v_mul_f32_e32 v4, v27, v5
	v_pk_add_f32 v[6:7], v[26:27], 1.0 op_sel_hi:[1,0] neg_lo:[1,0] neg_hi:[1,0]
	s_nop 0
	v_pk_mul_f32 v[28:29], v[6:7], v[4:5]
	v_mul_f32_e32 v5, v26, v4
	v_mul_f32_e32 v4, v25, v5
	v_pk_add_f32 v[6:7], v[24:25], 1.0 op_sel_hi:[1,0] neg_lo:[1,0] neg_hi:[1,0]
	s_nop 0
	v_pk_mul_f32 v[26:27], v[6:7], v[4:5]
	v_mul_f32_e32 v5, v24, v4
	v_mul_f32_e32 v4, v23, v5
	v_pk_add_f32 v[6:7], v[22:23], 1.0 op_sel_hi:[1,0] neg_lo:[1,0] neg_hi:[1,0]
	s_nop 0
	v_pk_mul_f32 v[24:25], v[6:7], v[4:5]
	v_mul_f32_e32 v5, v22, v4
	v_mul_f32_e32 v4, v21, v5
	v_pk_add_f32 v[6:7], v[20:21], 1.0 op_sel_hi:[1,0] neg_lo:[1,0] neg_hi:[1,0]
	s_nop 0
	v_pk_mul_f32 v[22:23], v[6:7], v[4:5]
	v_mul_f32_e32 v5, v20, v4
	v_mul_f32_e32 v4, v19, v5
	v_pk_add_f32 v[6:7], v[18:19], 1.0 op_sel_hi:[1,0] neg_lo:[1,0] neg_hi:[1,0]
	s_nop 0
	v_pk_mul_f32 v[20:21], v[6:7], v[4:5]
	v_mul_f32_e32 v5, v18, v4
	v_mul_f32_e32 v4, v15, v5
	v_pk_add_f32 v[6:7], v[14:15], 1.0 op_sel_hi:[1,0] neg_lo:[1,0] neg_hi:[1,0]
	s_nop 0
	v_pk_mul_f32 v[18:19], v[6:7], v[4:5]
	v_mul_f32_e32 v5, v14, v4
	v_mul_f32_e32 v4, v13, v5
	v_pk_add_f32 v[6:7], v[12:13], 1.0 op_sel_hi:[1,0] neg_lo:[1,0] neg_hi:[1,0]
	s_nop 0
	v_pk_mul_f32 v[6:7], v[6:7], v[4:5]
	v_mul_f32_e32 v5, v12, v4
	v_mul_f32_e32 v4, v11, v5
	v_pk_add_f32 v[12:13], v[10:11], 1.0 op_sel_hi:[1,0] neg_lo:[1,0] neg_hi:[1,0]
	v_mul_f32_e32 v11, v10, v4
	v_pk_mul_f32 v[12:13], v[12:13], v[4:5]
	v_mul_f32_e32 v10, v9, v11
	v_pk_add_f32 v[4:5], v[8:9], 1.0 op_sel_hi:[1,0] neg_lo:[1,0] neg_hi:[1,0]
	v_cvt_pk_bf16_f32 v6, v6, v7
	v_pk_mul_f32 v[4:5], v[4:5], v[10:11]
	v_cvt_pk_bf16_f32 v7, v18, v19
	v_cvt_pk_bf16_f32 v4, v4, v5
	v_cvt_pk_bf16_f32 v5, v12, v13
	ds_write_b128 v0, v[4:7]
	v_cvt_pk_bf16_f32 v4, v20, v21
	v_cvt_pk_bf16_f32 v5, v22, v23
	v_cvt_pk_bf16_f32 v6, v24, v25
	v_cvt_pk_bf16_f32 v7, v26, v27
	ds_write_b128 v0, v[4:7] offset:16
	v_cvt_pk_bf16_f32 v4, v28, v29
	v_cvt_pk_bf16_f32 v5, v30, v31
	v_cvt_pk_bf16_f32 v6, v32, v33
	v_cvt_pk_bf16_f32 v7, v36, v37
	ds_write_b128 v0, v[4:7] offset:32
	v_cvt_pk_bf16_f32 v4, v38, v39
	v_cvt_pk_bf16_f32 v5, v40, v41
	v_cvt_pk_bf16_f32 v6, v42, v43
	v_cvt_pk_bf16_f32 v7, v16, v17
	ds_write_b128 v0, v[4:7] offset:48
	v_mul_f32_e32 v0, v8, v10
	v_ashrrev_i32_e32 v4, 5, v34
	global_store_dword v[2:3], v0, off sc1
	v_lshlrev_b32_e32 v0, 4, v4
	v_add_u32_e32 v47, vcc_lo, v0
	v_mad_u32_u24 v18, v46, s14, v47
	ds_read_b128 v[22:25], v18 offset:9216
	ds_read_b128 v[42:45], v18
	ds_read_b128 v[38:41], v18 offset:32
	v_lshlrev_b32_e32 v78, 2, v4
	s_waitcnt lgkmcnt(1)
	v_mfma_f32_32x32x16_bf16 v[2:17], v[42:45], v[22:25], 0
	ds_read_b128 v[26:29], v18 offset:9248
	ds_read_b128 v[54:57], v18 offset:64
	ds_read_b128 v[30:33], v18 offset:9280
	ds_read_b128 v[50:53], v18 offset:96
	ds_read_b128 v[18:21], v18 offset:9312
	v_and_b32_e32 v66, 48, v0
	v_or_b32_e32 v0, v66, v79
	v_mul_u32_u24_e32 v0, 0x2100, v0
	v_and_b32_e32 v34, -16, v78
	s_waitcnt lgkmcnt(4)
	v_mfma_f32_32x32x16_bf16 v[2:17], v[38:41], v[26:29], v[2:17]
	v_ashrrev_i32_e32 v35, 31, v34
	v_lshlrev_b32_e32 v0, 2, v0
	v_lshl_add_u64 v[36:37], s[0:1], 0, v[0:1]
	v_lshlrev_b64 v[72:73], 2, v[34:35]
	v_lshl_add_u64 v[34:35], v[36:37], 0, v[72:73]
	v_lshlrev_b32_e32 v0, 2, v48
	v_lshl_add_u64 v[58:59], v[34:35], 0, v[0:1]
	s_waitcnt lgkmcnt(2)
	v_mfma_f32_32x32x16_bf16 v[2:17], v[54:57], v[30:33], v[2:17]
	v_or_b32_e32 v68, 4, v66
	v_mov_b32_e32 v35, v1
	v_or_b32_e32 v70, 8, v66
	v_or_b32_e32 v81, 12, v66
	v_mad_u32_u24 v90, v67, s14, v47
	s_waitcnt lgkmcnt(0)
	v_mfma_f32_32x32x16_bf16 v[2:17], v[50:53], v[18:21], v[2:17]
	s_nop 11
	global_store_dword v[58:59], v2, off sc1
	v_or_b32_e32 v2, v68, v79
	v_mul_u32_u24_e32 v2, 0x2100, v2
	v_lshlrev_b32_e32 v34, 2, v2
	v_lshl_add_u64 v[34:35], s[0:1], 0, v[34:35]
	v_lshl_add_u64 v[34:35], v[34:35], 0, v[72:73]
	v_or_b32_e32 v2, v70, v79
	v_lshl_add_u64 v[60:61], v[34:35], 0, v[0:1]
	v_mul_u32_u24_e32 v2, 0x2100, v2
	global_store_dword v[60:61], v3, off sc1
	v_lshlrev_b32_e32 v2, 2, v2
	v_mov_b32_e32 v3, v1
	v_lshl_add_u64 v[2:3], s[0:1], 0, v[2:3]
	v_lshl_add_u64 v[2:3], v[2:3], 0, v[72:73]
	v_lshl_add_u64 v[62:63], v[2:3], 0, v[0:1]
	v_or_b32_e32 v2, v81, v79
	v_mul_u32_u24_e32 v2, 0x2100, v2
	v_lshlrev_b32_e32 v2, 2, v2
	v_mov_b32_e32 v3, v1
	v_lshl_add_u64 v[2:3], s[0:1], 0, v[2:3]
	v_lshl_add_u64 v[2:3], v[2:3], 0, v[72:73]
	v_lshl_add_u64 v[64:65], v[2:3], 0, v[0:1]
	v_add_u32_e32 v2, 8, v78
	v_lshlrev_b32_e32 v3, 2, v2
	v_and_b32_e32 v82, 48, v3
	v_or_b32_e32 v3, v82, v79
	global_store_dword v[62:63], v4, off sc1
	v_mul_u32_u24_e32 v4, 0x2100, v3
	v_and_b32_e32 v2, -16, v2
	global_store_dword v[64:65], v5, off sc1
	v_ashrrev_i32_e32 v3, 31, v2
	v_lshlrev_b32_e32 v4, 2, v4
	v_mov_b32_e32 v5, v1
	v_lshl_add_u64 v[4:5], s[0:1], 0, v[4:5]
	v_lshlrev_b64 v[74:75], 2, v[2:3]
	v_lshl_add_u64 v[2:3], v[4:5], 0, v[74:75]
	v_lshl_add_u64 v[2:3], v[2:3], 0, v[0:1]
	v_or_b32_e32 v83, 4, v82
	global_store_dword v[2:3], v6, off sc1
	v_or_b32_e32 v2, v83, v79
	v_mul_u32_u24_e32 v2, 0x2100, v2
	v_lshlrev_b32_e32 v2, 2, v2
	v_mov_b32_e32 v3, v1
	v_lshl_add_u64 v[2:3], s[0:1], 0, v[2:3]
	v_lshl_add_u64 v[2:3], v[2:3], 0, v[74:75]
	v_lshl_add_u64 v[2:3], v[2:3], 0, v[0:1]
	v_or_b32_e32 v84, 8, v82
	global_store_dword v[2:3], v7, off sc1
	v_or_b32_e32 v2, v84, v79
	v_mul_u32_u24_e32 v2, 0x2100, v2
	v_lshlrev_b32_e32 v2, 2, v2
	v_mov_b32_e32 v3, v1
	v_lshl_add_u64 v[2:3], s[0:1], 0, v[2:3]
	v_lshl_add_u64 v[2:3], v[2:3], 0, v[74:75]
	v_lshl_add_u64 v[2:3], v[2:3], 0, v[0:1]
	v_or_b32_e32 v85, 12, v82
	global_store_dword v[2:3], v8, off sc1
	v_or_b32_e32 v2, v85, v79
	v_mul_u32_u24_e32 v2, 0x2100, v2
	v_lshlrev_b32_e32 v2, 2, v2
	v_mov_b32_e32 v3, v1
	v_lshl_add_u64 v[2:3], s[0:1], 0, v[2:3]
	v_lshl_add_u64 v[2:3], v[2:3], 0, v[74:75]
	v_lshl_add_u64 v[2:3], v[2:3], 0, v[0:1]
	global_store_dword v[2:3], v9, off sc1
	global_store_dword v[58:59], v10, off offset:64 sc1
	global_store_dword v[60:61], v11, off offset:64 sc1
	global_store_dword v[62:63], v12, off offset:64 sc1
	global_store_dword v[64:65], v13, off offset:64 sc1
	v_add_u32_e32 v2, 24, v78
	v_lshlrev_b32_e32 v3, 2, v2
	v_and_b32_e32 v86, 48, v3
	v_or_b32_e32 v3, v86, v79
	v_mul_u32_u24_e32 v4, 0x2100, v3
	v_and_b32_e32 v2, -16, v2
	v_ashrrev_i32_e32 v3, 31, v2
	v_lshlrev_b32_e32 v4, 2, v4
	v_mov_b32_e32 v5, v1
	v_lshl_add_u64 v[4:5], s[0:1], 0, v[4:5]
	v_lshlrev_b64 v[76:77], 2, v[2:3]
	v_lshl_add_u64 v[2:3], v[4:5], 0, v[76:77]
	v_lshl_add_u64 v[2:3], v[2:3], 0, v[0:1]
	v_or_b32_e32 v87, 4, v86
	global_store_dword v[2:3], v14, off sc1
	v_or_b32_e32 v2, v87, v79
	v_mul_u32_u24_e32 v2, 0x2100, v2
	v_lshlrev_b32_e32 v2, 2, v2
	v_mov_b32_e32 v3, v1
	v_lshl_add_u64 v[2:3], s[0:1], 0, v[2:3]
	v_lshl_add_u64 v[2:3], v[2:3], 0, v[76:77]
	v_lshl_add_u64 v[2:3], v[2:3], 0, v[0:1]
	v_or_b32_e32 v88, 8, v86
	global_store_dword v[2:3], v15, off sc1
	v_or_b32_e32 v2, v88, v79
	v_mul_u32_u24_e32 v2, 0x2100, v2
	v_lshlrev_b32_e32 v2, 2, v2
	v_mov_b32_e32 v3, v1
	v_lshl_add_u64 v[2:3], s[0:1], 0, v[2:3]
	v_lshl_add_u64 v[2:3], v[2:3], 0, v[76:77]
	v_lshl_add_u64 v[2:3], v[2:3], 0, v[0:1]
	v_or_b32_e32 v89, 12, v86
	global_store_dword v[2:3], v16, off sc1
	v_or_b32_e32 v2, v89, v79
	v_mul_u32_u24_e32 v2, 0x2100, v2
	v_lshlrev_b32_e32 v2, 2, v2
	v_mov_b32_e32 v3, v1
	v_lshl_add_u64 v[2:3], s[0:1], 0, v[2:3]
	v_lshl_add_u64 v[2:3], v[2:3], 0, v[76:77]
	v_lshl_add_u64 v[2:3], v[2:3], 0, v[0:1]
	global_store_dword v[2:3], v17, off sc1
	ds_read_b128 v[46:49], v90 offset:9216
	ds_read_b128 v[34:37], v90 offset:9248
	s_waitcnt lgkmcnt(1)
	v_mfma_f32_32x32x16_bf16 v[2:17], v[42:45], v[46:49], 0
	ds_read_b128 v[42:45], v90 offset:9280
	s_waitcnt lgkmcnt(1)
	v_mfma_f32_32x32x16_bf16 v[2:17], v[38:41], v[34:37], v[2:17]
	ds_read_b128 v[38:41], v90 offset:9312
	s_waitcnt lgkmcnt(1)
	v_mfma_f32_32x32x16_bf16 v[2:17], v[54:57], v[42:45], v[2:17]
	s_waitcnt lgkmcnt(0)
	v_mfma_f32_32x32x16_bf16 v[2:17], v[50:53], v[38:41], v[2:17]
	v_or_b32_e32 v50, v66, v80
	v_mul_u32_u24_e32 v50, 0x2100, v50
	v_lshlrev_b32_e32 v50, 2, v50
	v_mov_b32_e32 v51, v1
	v_lshl_add_u64 v[50:51], s[0:1], 0, v[50:51]
	v_lshl_add_u64 v[50:51], v[50:51], 0, v[72:73]
	v_lshl_add_u64 v[66:67], v[50:51], 0, v[0:1]
	s_nop 4
	global_store_dword v[66:67], v2, off sc1
	v_or_b32_e32 v2, v68, v80
	v_mul_u32_u24_e32 v2, 0x2100, v2
	v_lshlrev_b32_e32 v50, 2, v2
	v_mov_b32_e32 v51, v1
	v_lshl_add_u64 v[50:51], s[0:1], 0, v[50:51]
	v_lshl_add_u64 v[50:51], v[50:51], 0, v[72:73]
	v_or_b32_e32 v2, v70, v80
	v_lshl_add_u64 v[68:69], v[50:51], 0, v[0:1]
	v_mul_u32_u24_e32 v2, 0x2100, v2
	global_store_dword v[68:69], v3, off sc1
	v_lshlrev_b32_e32 v2, 2, v2
	v_mov_b32_e32 v3, v1
	v_lshl_add_u64 v[2:3], s[0:1], 0, v[2:3]
	v_lshl_add_u64 v[2:3], v[2:3], 0, v[72:73]
	v_lshl_add_u64 v[70:71], v[2:3], 0, v[0:1]
	v_or_b32_e32 v2, v81, v80
	v_mul_u32_u24_e32 v2, 0x2100, v2
	v_lshlrev_b32_e32 v2, 2, v2
	v_mov_b32_e32 v3, v1
	v_lshl_add_u64 v[2:3], s[0:1], 0, v[2:3]
	v_lshl_add_u64 v[2:3], v[2:3], 0, v[72:73]
	v_lshl_add_u64 v[72:73], v[2:3], 0, v[0:1]
	v_or_b32_e32 v2, v82, v80
	v_mul_u32_u24_e32 v2, 0x2100, v2
	v_lshlrev_b32_e32 v2, 2, v2
	v_mov_b32_e32 v3, v1
	v_lshl_add_u64 v[2:3], s[0:1], 0, v[2:3]
	v_lshl_add_u64 v[2:3], v[2:3], 0, v[74:75]
	v_lshl_add_u64 v[2:3], v[2:3], 0, v[0:1]
	global_store_dword v[70:71], v4, off sc1
	global_store_dword v[72:73], v5, off sc1
	global_store_dword v[2:3], v6, off sc1
	v_or_b32_e32 v2, v83, v80
	v_mul_u32_u24_e32 v2, 0x2100, v2
	v_lshlrev_b32_e32 v2, 2, v2
	v_mov_b32_e32 v3, v1
	v_lshl_add_u64 v[2:3], s[0:1], 0, v[2:3]
	v_lshl_add_u64 v[2:3], v[2:3], 0, v[74:75]
	v_lshl_add_u64 v[2:3], v[2:3], 0, v[0:1]
	global_store_dword v[2:3], v7, off sc1
	v_or_b32_e32 v2, v84, v80
	v_mul_u32_u24_e32 v2, 0x2100, v2
	v_lshlrev_b32_e32 v2, 2, v2
	v_mov_b32_e32 v3, v1
	v_lshl_add_u64 v[2:3], s[0:1], 0, v[2:3]
	v_lshl_add_u64 v[2:3], v[2:3], 0, v[74:75]
	v_lshl_add_u64 v[2:3], v[2:3], 0, v[0:1]
	global_store_dword v[2:3], v8, off sc1
	v_or_b32_e32 v2, v85, v80
	v_mul_u32_u24_e32 v2, 0x2100, v2
	v_lshlrev_b32_e32 v2, 2, v2
	v_mov_b32_e32 v3, v1
	v_lshl_add_u64 v[2:3], s[0:1], 0, v[2:3]
	v_lshl_add_u64 v[2:3], v[2:3], 0, v[74:75]
	v_lshl_add_u64 v[2:3], v[2:3], 0, v[0:1]
	global_store_dword v[2:3], v9, off sc1
	global_store_dword v[66:67], v10, off offset:64 sc1
	global_store_dword v[68:69], v11, off offset:64 sc1
	global_store_dword v[70:71], v12, off offset:64 sc1
	global_store_dword v[72:73], v13, off offset:64 sc1
	v_or_b32_e32 v2, v86, v80
	v_mul_u32_u24_e32 v2, 0x2100, v2
	v_lshlrev_b32_e32 v2, 2, v2
	v_mov_b32_e32 v3, v1
	v_lshl_add_u64 v[2:3], s[0:1], 0, v[2:3]
	v_lshl_add_u64 v[2:3], v[2:3], 0, v[76:77]
	v_lshl_add_u64 v[2:3], v[2:3], 0, v[0:1]
	global_store_dword v[2:3], v14, off sc1
	v_or_b32_e32 v2, v87, v80
	v_mul_u32_u24_e32 v2, 0x2100, v2
	v_lshlrev_b32_e32 v2, 2, v2
	v_mov_b32_e32 v3, v1
	v_lshl_add_u64 v[2:3], s[0:1], 0, v[2:3]
	v_lshl_add_u64 v[2:3], v[2:3], 0, v[76:77]
	v_lshl_add_u64 v[2:3], v[2:3], 0, v[0:1]
	global_store_dword v[2:3], v15, off sc1
	v_or_b32_e32 v2, v88, v80
	v_mul_u32_u24_e32 v2, 0x2100, v2
	v_lshlrev_b32_e32 v2, 2, v2
	v_mov_b32_e32 v3, v1
	v_lshl_add_u64 v[2:3], s[0:1], 0, v[2:3]
	v_lshl_add_u64 v[2:3], v[2:3], 0, v[76:77]
	v_lshl_add_u64 v[2:3], v[2:3], 0, v[0:1]
	global_store_dword v[2:3], v16, off sc1
	v_or_b32_e32 v2, v89, v80
	v_mul_u32_u24_e32 v2, 0x2100, v2
	v_lshlrev_b32_e32 v2, 2, v2
	v_mov_b32_e32 v3, v1
	v_lshl_add_u64 v[2:3], s[0:1], 0, v[2:3]
	v_lshl_add_u64 v[2:3], v[2:3], 0, v[76:77]
	v_lshl_add_u64 v[2:3], v[2:3], 0, v[0:1]
	global_store_dword v[2:3], v17, off sc1
	ds_read_b128 v[54:57], v90
	ds_read_b128 v[50:53], v90 offset:32
	s_waitcnt lgkmcnt(1)
	v_mfma_f32_32x32x16_bf16 v[2:17], v[54:57], v[22:25], 0
	ds_read_b128 v[22:25], v90 offset:64
	s_waitcnt lgkmcnt(1)
	v_mfma_f32_32x32x16_bf16 v[2:17], v[50:53], v[26:29], v[2:17]
	ds_read_b128 v[26:29], v90 offset:96
	s_waitcnt lgkmcnt(1)
	v_mfma_f32_32x32x16_bf16 v[2:17], v[22:25], v[30:33], v[2:17]
	s_waitcnt lgkmcnt(0)
	v_mfma_f32_32x32x16_bf16 v[2:17], v[26:29], v[18:21], v[2:17]
	s_nop 11
	global_store_dword v[58:59], v2, off offset:128 sc1
	global_store_dword v[60:61], v3, off offset:128 sc1
	global_store_dword v[62:63], v4, off offset:128 sc1
	global_store_dword v[64:65], v5, off offset:128 sc1
	v_add_u32_e32 v2, 40, v78
	v_lshlrev_b32_e32 v3, 2, v2
	v_and_b32_e32 v30, 48, v3
	v_or_b32_e32 v3, v30, v79
	v_mul_u32_u24_e32 v4, 0x2100, v3
	v_and_b32_e32 v2, -16, v2
	v_ashrrev_i32_e32 v3, 31, v2
	v_lshlrev_b32_e32 v4, 2, v4
	v_mov_b32_e32 v5, v1
	v_lshl_add_u64 v[4:5], s[0:1], 0, v[4:5]
	v_lshlrev_b64 v[18:19], 2, v[2:3]
	v_lshl_add_u64 v[2:3], v[4:5], 0, v[18:19]
	v_lshl_add_u64 v[2:3], v[2:3], 0, v[0:1]
	v_or_b32_e32 v31, 4, v30
	global_store_dword v[2:3], v6, off sc1
	v_or_b32_e32 v2, v31, v79
	v_mul_u32_u24_e32 v2, 0x2100, v2
	v_lshlrev_b32_e32 v2, 2, v2
	v_mov_b32_e32 v3, v1
	v_lshl_add_u64 v[2:3], s[0:1], 0, v[2:3]
	v_lshl_add_u64 v[2:3], v[2:3], 0, v[18:19]
	v_lshl_add_u64 v[2:3], v[2:3], 0, v[0:1]
	v_or_b32_e32 v32, 8, v30
	global_store_dword v[2:3], v7, off sc1
	v_or_b32_e32 v2, v32, v79
	v_mul_u32_u24_e32 v2, 0x2100, v2
	v_lshlrev_b32_e32 v2, 2, v2
	v_mov_b32_e32 v3, v1
	v_lshl_add_u64 v[2:3], s[0:1], 0, v[2:3]
	v_lshl_add_u64 v[2:3], v[2:3], 0, v[18:19]
	v_lshl_add_u64 v[2:3], v[2:3], 0, v[0:1]
	v_or_b32_e32 v33, 12, v30
	global_store_dword v[2:3], v8, off sc1
	v_or_b32_e32 v2, v33, v79
	v_mul_u32_u24_e32 v2, 0x2100, v2
	v_lshlrev_b32_e32 v2, 2, v2
	v_mov_b32_e32 v3, v1
	v_lshl_add_u64 v[2:3], s[0:1], 0, v[2:3]
	v_lshl_add_u64 v[2:3], v[2:3], 0, v[18:19]
	v_lshl_add_u64 v[2:3], v[2:3], 0, v[0:1]
	global_store_dword v[2:3], v9, off sc1
	global_store_dword v[58:59], v10, off offset:192 sc1
	global_store_dword v[60:61], v11, off offset:192 sc1
	global_store_dword v[62:63], v12, off offset:192 sc1
	global_store_dword v[64:65], v13, off offset:192 sc1
	v_add_u32_e32 v2, 56, v78
	v_lshlrev_b32_e32 v3, 2, v2
	v_and_b32_e32 v58, 48, v3
	v_or_b32_e32 v3, v58, v79
	v_mul_u32_u24_e32 v4, 0x2100, v3
	v_and_b32_e32 v2, -16, v2
	v_ashrrev_i32_e32 v3, 31, v2
	v_lshlrev_b32_e32 v4, 2, v4
	v_mov_b32_e32 v5, v1
	v_lshl_add_u64 v[4:5], s[0:1], 0, v[4:5]
	v_lshlrev_b64 v[20:21], 2, v[2:3]
	v_lshl_add_u64 v[2:3], v[4:5], 0, v[20:21]
	v_lshl_add_u64 v[2:3], v[2:3], 0, v[0:1]
	v_or_b32_e32 v59, 4, v58
	global_store_dword v[2:3], v14, off sc1
	v_or_b32_e32 v2, v59, v79
	v_mul_u32_u24_e32 v2, 0x2100, v2
	v_lshlrev_b32_e32 v2, 2, v2
	v_mov_b32_e32 v3, v1
	v_lshl_add_u64 v[2:3], s[0:1], 0, v[2:3]
	v_lshl_add_u64 v[2:3], v[2:3], 0, v[20:21]
	v_lshl_add_u64 v[2:3], v[2:3], 0, v[0:1]
	v_or_b32_e32 v60, 8, v58
	global_store_dword v[2:3], v15, off sc1
	v_or_b32_e32 v2, v60, v79
	v_mul_u32_u24_e32 v2, 0x2100, v2
	v_lshlrev_b32_e32 v2, 2, v2
	v_mov_b32_e32 v3, v1
	v_lshl_add_u64 v[2:3], s[0:1], 0, v[2:3]
	v_lshl_add_u64 v[2:3], v[2:3], 0, v[20:21]
	v_lshl_add_u64 v[2:3], v[2:3], 0, v[0:1]
	v_or_b32_e32 v61, 12, v58
	global_store_dword v[2:3], v16, off sc1
	v_or_b32_e32 v2, v61, v79
	v_mul_u32_u24_e32 v2, 0x2100, v2
	v_lshlrev_b32_e32 v2, 2, v2
	v_mov_b32_e32 v3, v1
	v_lshl_add_u64 v[2:3], s[0:1], 0, v[2:3]
	v_lshl_add_u64 v[2:3], v[2:3], 0, v[20:21]
	v_lshl_add_u64 v[2:3], v[2:3], 0, v[0:1]
	global_store_dword v[2:3], v17, off sc1
	v_mfma_f32_32x32x16_bf16 v[2:17], v[54:57], v[46:49], 0
	v_mfma_f32_32x32x16_bf16 v[2:17], v[50:53], v[34:37], v[2:17]
	v_mfma_f32_32x32x16_bf16 v[2:17], v[22:25], v[42:45], v[2:17]
	v_mfma_f32_32x32x16_bf16 v[2:17], v[26:29], v[38:41], v[2:17]
	s_nop 11
	global_store_dword v[66:67], v2, off offset:128 sc1
	global_store_dword v[68:69], v3, off offset:128 sc1
	global_store_dword v[70:71], v4, off offset:128 sc1
	global_store_dword v[72:73], v5, off offset:128 sc1
	v_or_b32_e32 v2, v30, v80
	v_mul_u32_u24_e32 v2, 0x2100, v2
	v_lshlrev_b32_e32 v2, 2, v2
	v_mov_b32_e32 v3, v1
	v_lshl_add_u64 v[2:3], s[0:1], 0, v[2:3]
	v_lshl_add_u64 v[2:3], v[2:3], 0, v[18:19]
	v_lshl_add_u64 v[2:3], v[2:3], 0, v[0:1]
	global_store_dword v[2:3], v6, off sc1
	v_or_b32_e32 v2, v31, v80
	v_mul_u32_u24_e32 v2, 0x2100, v2
	v_lshlrev_b32_e32 v2, 2, v2
	v_mov_b32_e32 v3, v1
	v_lshl_add_u64 v[2:3], s[0:1], 0, v[2:3]
	v_lshl_add_u64 v[2:3], v[2:3], 0, v[18:19]
	v_lshl_add_u64 v[2:3], v[2:3], 0, v[0:1]
	global_store_dword v[2:3], v7, off sc1
	v_or_b32_e32 v2, v32, v80
	v_mul_u32_u24_e32 v2, 0x2100, v2
	v_lshlrev_b32_e32 v2, 2, v2
	v_mov_b32_e32 v3, v1
	v_lshl_add_u64 v[2:3], s[0:1], 0, v[2:3]
	v_lshl_add_u64 v[2:3], v[2:3], 0, v[18:19]
	v_lshl_add_u64 v[2:3], v[2:3], 0, v[0:1]
	global_store_dword v[2:3], v8, off sc1
	v_or_b32_e32 v2, v33, v80
	v_mul_u32_u24_e32 v2, 0x2100, v2
	v_lshlrev_b32_e32 v2, 2, v2
	v_mov_b32_e32 v3, v1
	v_lshl_add_u64 v[2:3], s[0:1], 0, v[2:3]
	v_lshl_add_u64 v[2:3], v[2:3], 0, v[18:19]
	v_lshl_add_u64 v[2:3], v[2:3], 0, v[0:1]
	global_store_dword v[2:3], v9, off sc1
	global_store_dword v[66:67], v10, off offset:192 sc1
	global_store_dword v[68:69], v11, off offset:192 sc1
	global_store_dword v[70:71], v12, off offset:192 sc1
	global_store_dword v[72:73], v13, off offset:192 sc1
	v_or_b32_e32 v2, v58, v80
	v_mul_u32_u24_e32 v2, 0x2100, v2
	v_lshlrev_b32_e32 v2, 2, v2
	v_mov_b32_e32 v3, v1
	v_lshl_add_u64 v[2:3], s[0:1], 0, v[2:3]
	v_lshl_add_u64 v[2:3], v[2:3], 0, v[20:21]
	v_lshl_add_u64 v[2:3], v[2:3], 0, v[0:1]
	global_store_dword v[2:3], v14, off sc1
	v_or_b32_e32 v2, v59, v80
	v_mul_u32_u24_e32 v2, 0x2100, v2
	v_lshlrev_b32_e32 v2, 2, v2
	v_mov_b32_e32 v3, v1
	v_lshl_add_u64 v[2:3], s[0:1], 0, v[2:3]
	v_lshl_add_u64 v[2:3], v[2:3], 0, v[20:21]
	v_lshl_add_u64 v[2:3], v[2:3], 0, v[0:1]
	global_store_dword v[2:3], v15, off sc1
	v_or_b32_e32 v2, v60, v80
	v_mul_u32_u24_e32 v2, 0x2100, v2
	v_lshlrev_b32_e32 v2, 2, v2
	v_mov_b32_e32 v3, v1
	v_lshl_add_u64 v[2:3], s[0:1], 0, v[2:3]
	v_lshl_add_u64 v[2:3], v[2:3], 0, v[20:21]
	v_lshl_add_u64 v[2:3], v[2:3], 0, v[0:1]
	global_store_dword v[2:3], v16, off sc1
	v_or_b32_e32 v2, v61, v80
	v_mul_u32_u24_e32 v2, 0x2100, v2
	v_lshlrev_b32_e32 v2, 2, v2
	v_mov_b32_e32 v3, v1
	v_lshl_add_u64 v[2:3], s[0:1], 0, v[2:3]
	v_lshl_add_u64 v[2:3], v[2:3], 0, v[20:21]
	v_lshl_add_u64 v[2:3], v[2:3], 0, v[0:1]
	global_store_dword v[2:3], v17, off sc1
	v_readlane_b32 s0, v252, 22
	s_waitcnt lgkmcnt(0)
	s_add_i32 s2, s2, s0
	v_readlane_b32 s0, v254, 61
	s_sub_i32 s7, s7, s0
	v_readlane_b32 s1, v254, 62
	s_cmp_ge_i32 s2, s1
	s_cbranch_scc1 .LBB0_443

.LBB0_443:
	v_readlane_b32 s88, v254, 50
	s_lshl_b32 s44, s88, 6
	v_readlane_b32 s4, v254, 8
	s_ashr_i32 s45, s44, 31
	v_readlane_b32 s6, v254, 10
	v_readlane_b32 s7, v254, 11
	s_lshl_b64 s[0:1], s[44:45], 2
	s_mov_b64 s[2:3], s[6:7]
	s_add_u32 s0, s2, s0
	s_addc_u32 s1, s3, s1
	s_add_u32 s0, s0, 0x16000
	s_addc_u32 s1, s1, 0
	v_readlane_b32 s2, v252, 20
	v_readlane_b32 s89, v254, 51
	v_readlane_b32 s5, v254, 9
	v_writelane_b32 v254, s0, 54
	v_readlane_b32 s3, v252, 21
	s_and_b64 vcc, exec, s[2:3]
	v_writelane_b32 v254, s1, 55
	s_mov_b64 s[0:1], -1
	s_cbranch_vccz .LBB0_699
	s_waitcnt vmcnt(0)
	s_waitcnt vmcnt(0)
	s_barrier
	s_mov_b64 s[0:1], exec
	v_readlane_b32 s2, v252, 4
	v_readlane_b32 s3, v252, 5
	s_and_b64 s[2:3], s[0:1], s[2:3]
	s_mov_b64 exec, s[2:3]
	s_cbranch_execz .LBB0_461
	s_mov_b64 s[2:3], exec
	s_waitcnt vmcnt(0)
	v_mbcnt_lo_u32_b32 v0, s2, 0
	v_mbcnt_hi_u32_b32 v0, s3, v0
	v_cmp_eq_u32_e32 vcc, 0, v0
	s_and_saveexec_b64 s[4:5], vcc
	s_cbranch_execz .LBB0_447
	s_bcnt1_i32_b64 s2, s[2:3]
	v_mov_b32_e32 v0, s2
	v_readlane_b32 s2, v254, 54
	v_readlane_b32 s3, v254, 55
	s_nop 4
	global_atomic_add v1, v0, s[2:3]

.LBB0_466:
	v_readlane_b32 s56, v254, 8
	v_readlane_b32 s58, v254, 10
	v_readlane_b32 s59, v254, 11
	s_mov_b64 s[22:23], s[58:59]
	v_lshl_add_u64 v[10:11], s[22:23], 0, v[6:7]
	v_add_co_u32_e32 v106, vcc, 0xca00000, v10
	v_lshl_add_u64 v[14:15], s[22:23], 0, v[2:3]
	s_nop 0
	v_addc_co_u32_e32 v107, vcc, 0, v11, vcc
	v_add_co_u32_e32 v16, vcc, 0xeb00000, v14
	v_lshl_add_u64 v[12:13], s[22:23], 0, v[8:9]
	s_nop 0
	v_addc_co_u32_e32 v17, vcc, 0, v15, vcc
	v_add_co_u32_e32 v18, vcc, 0xca00000, v12
	v_lshl_add_u64 v[20:21], s[22:23], 0, v[4:5]
	s_nop 0
	v_addc_co_u32_e32 v19, vcc, 0, v13, vcc
	v_add_co_u32_e32 v22, vcc, 0xeb00000, v20
	v_readlane_b32 s57, v254, 9
	s_nop 0
	v_addc_co_u32_e32 v23, vcc, 0, v21, vcc
	global_load_dword v95, v[106:107], off
	global_load_dword v92, v[106:107], off offset:256
	global_load_dword v88, v[106:107], off offset:512
	global_load_dword v83, v[106:107], off offset:768
	global_load_dword v77, v[106:107], off offset:1024
	global_load_dword v72, v[106:107], off offset:1280
	global_load_dword v66, v[106:107], off offset:1536
	global_load_dword v62, v[106:107], off offset:1792
	global_load_dword v104, v[16:17], off
	global_load_dword v101, v[16:17], off offset:256
	global_load_dword v98, v[16:17], off offset:512
	global_load_dword v94, v[16:17], off offset:768
	global_load_dword v90, v[16:17], off offset:1024
	global_load_dword v85, v[16:17], off offset:1280
	global_load_dword v79, v[16:17], off offset:1536
	global_load_dword v71, v[16:17], off offset:1792
	global_load_dword v102, v[18:19], off
	global_load_dword v99, v[18:19], off offset:256
	global_load_dword v96, v[18:19], off offset:512
	global_load_dword v91, v[18:19], off offset:768
	global_load_dword v86, v[18:19], off offset:1024
	global_load_dword v80, v[18:19], off offset:1280
	global_load_dword v73, v[18:19], off offset:1536
	global_load_dword v67, v[18:19], off offset:1792
	global_load_dword v105, v[22:23], off
	global_load_dword v103, v[22:23], off offset:256
	global_load_dword v100, v[22:23], off offset:512
	global_load_dword v97, v[22:23], off offset:768
	global_load_dword v93, v[22:23], off offset:1024
	global_load_dword v89, v[22:23], off offset:1280
	global_load_dword v84, v[22:23], off offset:1536
	global_load_dword v76, v[22:23], off offset:1792
	global_load_dword v64, v[106:107], off offset:2048
	global_load_dword v60, v[106:107], off offset:2304
	global_load_dword v55, v[106:107], off offset:2560
	global_load_dword v51, v[106:107], off offset:2816
	global_load_dword v47, v[106:107], off offset:3072
	global_load_dword v44, v[106:107], off offset:3328
	global_load_dword v41, v[106:107], off offset:3584
	global_load_dword v40, v[106:107], off offset:3840
	global_load_dword v82, v[16:17], off offset:2048
	global_load_dword v75, v[16:17], off offset:2304
	global_load_dword v69, v[16:17], off offset:2560
	global_load_dword v63, v[16:17], off offset:2816
	global_load_dword v58, v[16:17], off offset:3072
	global_load_dword v53, v[16:17], off offset:3328
	global_load_dword v48, v[16:17], off offset:3584
	global_load_dword v43, v[16:17], off offset:3840
	global_load_dword v78, v[18:19], off offset:2048
	global_load_dword v70, v[18:19], off offset:2304
	global_load_dword v65, v[18:19], off offset:2560
	global_load_dword v59, v[18:19], off offset:2816
	global_load_dword v54, v[18:19], off offset:3072
	global_load_dword v50, v[18:19], off offset:3328
	global_load_dword v45, v[18:19], off offset:3584
	global_load_dword v42, v[18:19], off offset:3840
	global_load_dword v87, v[22:23], off offset:2048
	global_load_dword v81, v[22:23], off offset:2304
	global_load_dword v74, v[22:23], off offset:2560
	global_load_dword v68, v[22:23], off offset:2816
	global_load_dword v61, v[22:23], off offset:3072
	global_load_dword v57, v[22:23], off offset:3328
	global_load_dword v52, v[22:23], off offset:3584
	global_load_dword v46, v[22:23], off offset:3840
	v_add_co_u32_e32 v16, vcc, s10, v10
	s_nop 1
	v_addc_co_u32_e32 v17, vcc, 0, v11, vcc
	v_add_co_u32_e32 v108, vcc, s11, v14
	s_nop 1
	v_addc_co_u32_e32 v109, vcc, 0, v15, vcc
	v_add_co_u32_e32 v110, vcc, s10, v12
	s_nop 1
	v_addc_co_u32_e32 v111, vcc, 0, v13, vcc
	v_add_co_u32_e32 v112, vcc, s11, v20
	s_nop 1
	v_addc_co_u32_e32 v113, vcc, 0, v21, vcc
	global_load_dword v34, v[16:17], off
	global_load_dword v49, v[108:109], off
	global_load_dword v30, v[16:17], off offset:256
	global_load_dword v32, v[108:109], off offset:256
	global_load_dword v26, v[16:17], off offset:512
	global_load_dword v22, v[16:17], off offset:768
	global_load_dword v18, v[16:17], off offset:1024
	global_load_dword v14, v[16:17], off offset:1280
	global_load_dword v35, v[110:111], off
	global_load_dword v31, v[110:111], off offset:256
	global_load_dword v28, v[108:109], off offset:512
	global_load_dword v27, v[110:111], off offset:512
	global_load_dword v24, v[108:109], off offset:768
	global_load_dword v23, v[110:111], off offset:768
	global_load_dword v20, v[108:109], off offset:1024
	global_load_dword v16, v[108:109], off offset:1280
	global_load_dword v56, v[112:113], off
	global_load_dword v33, v[112:113], off offset:256
	global_load_dword v29, v[112:113], off offset:512
	global_load_dword v25, v[112:113], off offset:768
	global_load_dword v19, v[110:111], off offset:1024
	global_load_dword v21, v[112:113], off offset:1024
	global_load_dword v17, v[112:113], off offset:1280
	global_load_dword v15, v[110:111], off offset:1280
	s_nop 0
	global_store_dword v[106:107], v36, off sc1
	s_and_saveexec_b64 s[4:5], s[40:41]
	s_cbranch_execz .LBB0_468
	s_mov_b64 s[8:9], 0xca00000
	v_lshl_add_u64 v[106:107], v[12:13], 0, s[8:9]
	global_store_dword v[106:107], v37, off sc1
.LBB0_468:
	s_or_b64 exec, exec, s[4:5]
	v_lshl_add_u64 v[106:107], v[10:11], 0, s[48:49]
	s_waitcnt vmcnt(62)
	v_fmac_f32_e32 v95, v36, v104
	v_fmac_f32_e32 v102, v37, v105
	global_store_dword v[106:107], v95, off sc1
	s_and_saveexec_b64 s[4:5], s[40:41]
	s_cbranch_execz .LBB0_470
	v_lshl_add_u64 v[36:37], v[12:13], 0, s[48:49]
	global_store_dword v[36:37], v102, off sc1
.LBB0_470:
	s_or_b64 exec, exec, s[4:5]
	s_mov_b64 s[4:5], 0xca00200
	v_lshl_add_u64 v[36:37], v[10:11], 0, s[4:5]
	v_fmac_f32_e32 v92, v95, v101
	v_fmac_f32_e32 v99, v102, v103
	global_store_dword v[36:37], v92, off sc1
	s_and_saveexec_b64 s[4:5], s[40:41]
	s_cbranch_execz .LBB0_472
	s_mov_b64 s[8:9], 0xca00200
	v_lshl_add_u64 v[36:37], v[12:13], 0, s[8:9]
	global_store_dword v[36:37], v99, off sc1
.LBB0_472:
	s_or_b64 exec, exec, s[4:5]
	s_mov_b64 s[4:5], 0xca00300
	v_lshl_add_u64 v[36:37], v[10:11], 0, s[4:5]
	v_fmac_f32_e32 v88, v92, v98
	v_fmac_f32_e32 v96, v99, v100
	global_store_dword v[36:37], v88, off sc1
	s_and_saveexec_b64 s[4:5], s[40:41]
	s_cbranch_execz .LBB0_474
	s_mov_b64 s[8:9], 0xca00300
	v_lshl_add_u64 v[36:37], v[12:13], 0, s[8:9]
	global_store_dword v[36:37], v96, off sc1
.LBB0_474:
	s_or_b64 exec, exec, s[4:5]
	s_mov_b64 s[4:5], 0xca00400
	v_lshl_add_u64 v[36:37], v[10:11], 0, s[4:5]
	v_fmac_f32_e32 v83, v88, v94
	s_waitcnt vmcnt(62)
	v_fmac_f32_e32 v91, v96, v97
	global_store_dword v[36:37], v83, off sc1
	s_and_saveexec_b64 s[4:5], s[40:41]
	s_cbranch_execz .LBB0_476
	s_mov_b64 s[8:9], 0xca00400
	v_lshl_add_u64 v[36:37], v[12:13], 0, s[8:9]
	global_store_dword v[36:37], v91, off sc1
.LBB0_476:
	s_or_b64 exec, exec, s[4:5]
	s_mov_b64 s[4:5], 0xca00500
	v_lshl_add_u64 v[36:37], v[10:11], 0, s[4:5]
	v_fmac_f32_e32 v77, v83, v90
	v_fmac_f32_e32 v86, v91, v93
	global_store_dword v[36:37], v77, off sc1
	s_and_saveexec_b64 s[4:5], s[40:41]
	s_cbranch_execz .LBB0_478
	s_mov_b64 s[8:9], 0xca00500
	v_lshl_add_u64 v[36:37], v[12:13], 0, s[8:9]
	global_store_dword v[36:37], v86, off sc1
.LBB0_478:
	s_or_b64 exec, exec, s[4:5]
	s_mov_b64 s[4:5], 0xca00600
	v_lshl_add_u64 v[36:37], v[10:11], 0, s[4:5]
	v_fmac_f32_e32 v72, v77, v85
	v_fmac_f32_e32 v80, v86, v89
	global_store_dword v[36:37], v72, off sc1
	s_and_saveexec_b64 s[4:5], s[40:41]
	s_cbranch_execz .LBB0_480
	s_mov_b64 s[8:9], 0xca00600
	v_lshl_add_u64 v[36:37], v[12:13], 0, s[8:9]
	global_store_dword v[36:37], v80, off sc1
.LBB0_480:
	s_or_b64 exec, exec, s[4:5]
	s_mov_b64 s[4:5], 0xca00700
	v_lshl_add_u64 v[36:37], v[10:11], 0, s[4:5]
	v_fmac_f32_e32 v66, v72, v79
	s_waitcnt vmcnt(62)
	v_fmac_f32_e32 v73, v80, v84
	global_store_dword v[36:37], v66, off sc1
	s_and_saveexec_b64 s[4:5], s[40:41]
	s_cbranch_execz .LBB0_482
	s_mov_b64 s[8:9], 0xca00700
	v_lshl_add_u64 v[36:37], v[12:13], 0, s[8:9]
	global_store_dword v[36:37], v73, off sc1
.LBB0_482:
	s_or_b64 exec, exec, s[4:5]
	s_mov_b64 s[4:5], 0xca00800
	v_lshl_add_u64 v[36:37], v[10:11], 0, s[4:5]
	v_fmac_f32_e32 v62, v66, v71
	v_fmac_f32_e32 v67, v73, v76
	global_store_dword v[36:37], v62, off sc1
	s_and_saveexec_b64 s[4:5], s[40:41]
	s_cbranch_execz .LBB0_484
	s_mov_b64 s[8:9], 0xca00800
	v_lshl_add_u64 v[36:37], v[12:13], 0, s[8:9]
	global_store_dword v[36:37], v67, off sc1
.LBB0_484:
	s_or_b64 exec, exec, s[4:5]
	s_mov_b64 s[4:5], 0xca00900
	v_lshl_add_u64 v[36:37], v[10:11], 0, s[4:5]
	s_waitcnt vmcnt(56)
	v_fmac_f32_e32 v64, v62, v82
	s_waitcnt vmcnt(40)
	v_fmac_f32_e32 v78, v67, v87
	global_store_dword v[36:37], v64, off sc1
	s_and_saveexec_b64 s[4:5], s[40:41]
	s_cbranch_execz .LBB0_486
	s_mov_b64 s[8:9], 0xca00900
	v_lshl_add_u64 v[36:37], v[12:13], 0, s[8:9]
	global_store_dword v[36:37], v78, off sc1
.LBB0_486:
	s_or_b64 exec, exec, s[4:5]
	s_mov_b64 s[4:5], 0xca00a00
	v_lshl_add_u64 v[36:37], v[10:11], 0, s[4:5]
	v_fmac_f32_e32 v60, v64, v75
	s_waitcnt vmcnt(40)
	v_fmac_f32_e32 v70, v78, v81
	global_store_dword v[36:37], v60, off sc1
	s_and_saveexec_b64 s[4:5], s[40:41]
	s_cbranch_execz .LBB0_488
	s_mov_b64 s[8:9], 0xca00a00
	v_lshl_add_u64 v[36:37], v[12:13], 0, s[8:9]
	global_store_dword v[36:37], v70, off sc1
.LBB0_488:
	s_or_b64 exec, exec, s[4:5]
	s_mov_b64 s[4:5], 0xca00b00
	v_lshl_add_u64 v[36:37], v[10:11], 0, s[4:5]
	v_fmac_f32_e32 v55, v60, v69
	s_waitcnt vmcnt(40)
	v_fmac_f32_e32 v65, v70, v74
	global_store_dword v[36:37], v55, off sc1
	s_and_saveexec_b64 s[4:5], s[40:41]
	s_cbranch_execz .LBB0_490
	s_mov_b64 s[8:9], 0xca00b00
	v_lshl_add_u64 v[36:37], v[12:13], 0, s[8:9]
	global_store_dword v[36:37], v65, off sc1
.LBB0_490:
	s_or_b64 exec, exec, s[4:5]
	s_mov_b64 s[4:5], 0xca00c00
	v_lshl_add_u64 v[36:37], v[10:11], 0, s[4:5]
	v_fmac_f32_e32 v51, v55, v63
	s_waitcnt vmcnt(40)
	v_fmac_f32_e32 v59, v65, v68
	global_store_dword v[36:37], v51, off sc1
	s_and_saveexec_b64 s[4:5], s[40:41]
	s_cbranch_execz .LBB0_492
	s_mov_b64 s[8:9], 0xca00c00
	v_lshl_add_u64 v[36:37], v[12:13], 0, s[8:9]
	global_store_dword v[36:37], v59, off sc1
.LBB0_492:
	s_or_b64 exec, exec, s[4:5]
	s_mov_b64 s[4:5], 0xca00d00
	v_lshl_add_u64 v[36:37], v[10:11], 0, s[4:5]
	v_fmac_f32_e32 v47, v51, v58
	s_waitcnt vmcnt(40)
	v_fmac_f32_e32 v54, v59, v61
	global_store_dword v[36:37], v47, off sc1
	s_and_saveexec_b64 s[4:5], s[40:41]
	s_cbranch_execz .LBB0_494
	s_mov_b64 s[8:9], 0xca00d00
	v_lshl_add_u64 v[36:37], v[12:13], 0, s[8:9]
	global_store_dword v[36:37], v54, off sc1
.LBB0_494:
	s_or_b64 exec, exec, s[4:5]
	s_mov_b64 s[4:5], 0xca00e00
	v_lshl_add_u64 v[36:37], v[10:11], 0, s[4:5]
	v_fmac_f32_e32 v44, v47, v53
	s_waitcnt vmcnt(40)
	v_fmac_f32_e32 v50, v54, v57
	global_store_dword v[36:37], v44, off sc1
	s_and_saveexec_b64 s[4:5], s[40:41]
	s_cbranch_execz .LBB0_496
	s_mov_b64 s[8:9], 0xca00e00
	v_lshl_add_u64 v[36:37], v[12:13], 0, s[8:9]
	global_store_dword v[36:37], v50, off sc1
.LBB0_496:
	s_or_b64 exec, exec, s[4:5]
	s_mov_b64 s[4:5], 0xca00f00
	v_lshl_add_u64 v[36:37], v[10:11], 0, s[4:5]
	v_fmac_f32_e32 v41, v44, v48
	s_waitcnt vmcnt(40)
	v_fmac_f32_e32 v45, v50, v52
	global_store_dword v[36:37], v41, off sc1
	s_and_saveexec_b64 s[4:5], s[40:41]
	s_cbranch_execz .LBB0_498
	s_mov_b64 s[8:9], 0xca00f00
	v_lshl_add_u64 v[36:37], v[12:13], 0, s[8:9]
	global_store_dword v[36:37], v45, off sc1
.LBB0_498:
	s_or_b64 exec, exec, s[4:5]
	s_mov_b64 s[4:5], 0xca01000
	v_lshl_add_u64 v[36:37], v[10:11], 0, s[4:5]
	v_fmac_f32_e32 v40, v41, v43
	s_waitcnt vmcnt(40)
	v_fmac_f32_e32 v42, v45, v46
	global_store_dword v[36:37], v40, off sc1
	s_and_saveexec_b64 s[4:5], s[40:41]
	s_cbranch_execz .LBB0_500
	s_mov_b64 s[8:9], 0xca01000
	v_lshl_add_u64 v[36:37], v[12:13], 0, s[8:9]
	global_store_dword v[36:37], v42, off sc1
.LBB0_500:
	s_or_b64 exec, exec, s[4:5]
	s_mov_b64 s[4:5], 0xca01100
	s_waitcnt vmcnt(39)
	v_mul_f32_e32 v40, v40, v49
	s_waitcnt vmcnt(24)
	v_mul_f32_e32 v41, v42, v56
	v_lshl_add_u64 v[36:37], v[10:11], 0, s[4:5]
	v_pk_add_f32 v[34:35], v[40:41], v[34:35]
	global_store_dword v[36:37], v34, off sc1
	s_and_saveexec_b64 s[4:5], s[40:41]
	s_cbranch_execz .LBB0_502
	s_mov_b64 s[8:9], 0xca01100
	v_lshl_add_u64 v[36:37], v[12:13], 0, s[8:9]
	global_store_dword v[36:37], v35, off sc1
.LBB0_502:
	s_or_b64 exec, exec, s[4:5]
	s_mov_b64 s[4:5], 0xca01200
	v_lshl_add_u64 v[36:37], v[10:11], 0, s[4:5]
	s_waitcnt vmcnt(24)
	v_pk_fma_f32 v[30:31], v[34:35], v[32:33], v[30:31]
	global_store_dword v[36:37], v30, off sc1
	s_and_saveexec_b64 s[4:5], s[40:41]
	s_cbranch_execz .LBB0_504
	s_mov_b64 s[8:9], 0xca01200
	v_lshl_add_u64 v[32:33], v[12:13], 0, s[8:9]
	global_store_dword v[32:33], v31, off sc1
.LBB0_504:
	s_or_b64 exec, exec, s[4:5]
	s_mov_b64 s[4:5], 0xca01300
	v_lshl_add_u64 v[32:33], v[10:11], 0, s[4:5]
	s_waitcnt vmcnt(24)
	v_pk_fma_f32 v[26:27], v[30:31], v[28:29], v[26:27]
	global_store_dword v[32:33], v26, off sc1
	s_and_saveexec_b64 s[4:5], s[40:41]
	s_cbranch_execz .LBB0_506
	s_mov_b64 s[8:9], 0xca01300
	v_lshl_add_u64 v[28:29], v[12:13], 0, s[8:9]
	global_store_dword v[28:29], v27, off sc1
.LBB0_506:
	s_or_b64 exec, exec, s[4:5]
	s_mov_b64 s[4:5], 0xca01400
	v_lshl_add_u64 v[28:29], v[10:11], 0, s[4:5]
	s_waitcnt vmcnt(24)
	v_pk_fma_f32 v[22:23], v[26:27], v[24:25], v[22:23]
	global_store_dword v[28:29], v22, off sc1
	s_and_saveexec_b64 s[4:5], s[40:41]
	s_cbranch_execz .LBB0_508
	s_mov_b64 s[8:9], 0xca01400
	v_lshl_add_u64 v[24:25], v[12:13], 0, s[8:9]
	global_store_dword v[24:25], v23, off sc1
.LBB0_508:
	s_or_b64 exec, exec, s[4:5]
	s_mov_b64 s[4:5], 0xca01500
	v_lshl_add_u64 v[24:25], v[10:11], 0, s[4:5]
	s_waitcnt vmcnt(23)
	v_pk_fma_f32 v[10:11], v[22:23], v[20:21], v[18:19]
	global_store_dword v[24:25], v10, off sc1
	s_and_saveexec_b64 s[4:5], s[40:41]
	s_cbranch_execz .LBB0_465
	s_mov_b64 s[8:9], 0xca01500
	v_lshl_add_u64 v[12:13], v[12:13], 0, s[8:9]
	global_store_dword v[12:13], v11, off sc1
	s_branch .LBB0_465
.LBB0_510:
	s_or_b64 exec, exec, s[0:1]
	s_waitcnt vmcnt(0)
	s_barrier
	s_mov_b64 s[0:1], exec
	v_readlane_b32 s2, v252, 4
	v_readlane_b32 s3, v252, 5
	s_and_b64 s[2:3], s[0:1], s[2:3]
	s_mov_b64 exec, s[2:3]
	s_cbranch_execz .LBB0_527
	s_mov_b64 s[2:3], exec
	s_waitcnt vmcnt(0)
	s_waitcnt vmcnt(0)
	v_mbcnt_lo_u32_b32 v0, s2, 0
	v_mbcnt_hi_u32_b32 v0, s3, v0
	v_cmp_eq_u32_e32 vcc, 0, v0
	s_and_saveexec_b64 s[4:5], vcc
	s_cbranch_execz .LBB0_513
	s_bcnt1_i32_b64 s2, s[2:3]
	v_mov_b32_e32 v0, s2
	v_readlane_b32 s2, v254, 54
	v_readlane_b32 s3, v254, 55
	s_nop 4
	global_atomic_add v1, v0, s[2:3]
